# sc1 write-through also on LN, fin, convert and inproj q/k/v epilogue stores (on top of GEMM epilogue stores)
# baseline (speedup 1.0000x reference)
.LBB0_28:
	s_or_b64 exec, exec, s[6:7]
	global_load_dwordx4 v[16:19], v[34:35], off
	global_load_dwordx4 v[66:69], v[36:37], off
	v_pk_mul_f32 v[24:25], v[58:59], v[26:27] op_sel_hi:[1,0]
	v_pk_mul_f32 v[28:29], v[28:29], v[26:27] op_sel_hi:[1,0]
	v_cmp_lt_i32_e64 s[8:9], s34, v32
	v_cmp_ne_u32_e64 s[6:7], 1, v64
	s_andn2_b64 vcc, exec, s[22:23]
	s_waitcnt vmcnt(0)
	v_pk_fma_f32 v[16:17], v[24:25], v[16:17], v[66:67]
	v_pk_fma_f32 v[18:19], v[28:29], v[18:19], v[68:69]
	s_cbranch_vccnz .LBB0_30
	v_lshl_add_u64 v[24:25], v[48:49], 0, v[148:149]
	global_store_dwordx4 v[24:25], v[16:19], off sc1
.LBB0_30:
	v_add_u32_e32 v27, 0xffffe000, v32
	v_lshrrev_b32_e32 v27, 11, v27
	v_add_u32_e32 v27, 1, v27
	v_cndmask_b32_e64 v27, 0, v27, s[8:9]
	v_mad_u64_u32 v[28:29], s[8:9], v27, s35, v[38:39]
	s_mov_b64 s[14:15], 0x1000
	v_lshlrev_b64 v[24:25], 10, v[32:33]
	v_cmp_ne_u32_e64 s[8:9], 1, v65
	s_andn2_b64 vcc, exec, s[30:31]
	v_lshl_add_u64 v[30:31], v[28:29], 0, s[14:15]
	s_cbranch_vccnz .LBB0_32
	v_lshl_add_u64 v[58:59], v[30:31], 0, v[148:149]
	v_lshl_add_u64 v[66:67], v[28:29], 0, v[148:149]
	global_load_dwordx4 v[58:61], v[58:59], off
	s_nop 0
	global_load_dwordx4 v[66:69], v[66:67], off
	s_load_dwordx2 s[14:15], s[10:11], 0x120
	v_mov_b32_e32 v47, v149
	s_waitcnt vmcnt(1)
	v_pk_add_f32 v[58:59], v[58:59], 1.0 op_sel_hi:[1,0]
	s_waitcnt vmcnt(0)
	v_pk_fma_f32 v[16:17], v[16:17], v[58:59], v[66:67]
	v_pk_add_f32 v[58:59], v[60:61], 1.0 op_sel_hi:[1,0]
	v_cvt_pk_bf16_f32 v16, v16, v17
	v_pk_fma_f32 v[18:19], v[18:19], v[58:59], v[68:69]
	s_nop 0
	v_cvt_pk_bf16_f32 v17, v18, v19
	s_waitcnt lgkmcnt(0)
	v_lshl_add_u64 v[18:19], v[24:25], 1, s[14:15]
	v_lshl_add_u64 v[18:19], v[18:19], 0, v[46:47]
	v_add_co_u32_e32 v18, vcc, 0xe0c1000, v18
	s_nop 1
	v_addc_co_u32_e32 v19, vcc, 0, v19, vcc
	global_store_dwordx2 v[18:19], v[16:17], off sc1
.LBB0_32:
	global_load_dwordx4 v[16:19], v[34:35], off offset:1024
	s_nop 0
	global_load_dwordx4 v[58:61], v[36:37], off offset:1024
	v_mov_b32_e32 v27, v26
	v_pk_mul_f32 v[54:55], v[54:55], v[26:27]
	v_pk_mul_f32 v[56:57], v[56:57], v[26:27]
	s_and_b64 vcc, exec, s[6:7]
	s_waitcnt vmcnt(0)
	v_pk_fma_f32 v[16:17], v[54:55], v[16:17], v[58:59]
	v_pk_fma_f32 v[18:19], v[56:57], v[18:19], v[60:61]
	s_cbranch_vccnz .LBB0_34
	v_lshl_add_u64 v[54:55], v[48:49], 0, v[148:149]
	global_store_dwordx4 v[54:55], v[16:19], off offset:1024 sc1
.LBB0_34:
	s_and_b64 vcc, exec, s[8:9]
	s_cbranch_vccnz .LBB0_36
	v_mov_b32_e32 v41, v149
	v_lshl_add_u64 v[54:55], v[30:31], 0, v[40:41]
	v_lshl_add_u64 v[58:59], v[28:29], 0, v[148:149]
	global_load_dwordx4 v[54:57], v[54:55], off
	s_nop 0
	global_load_dwordx4 v[58:61], v[58:59], off offset:1024
	s_load_dwordx2 s[14:15], s[10:11], 0x120
	v_mov_b32_e32 v47, v149
	s_waitcnt vmcnt(1)
	v_pk_add_f32 v[54:55], v[54:55], 1.0 op_sel_hi:[1,0]
	s_waitcnt vmcnt(0)
	v_pk_fma_f32 v[16:17], v[16:17], v[54:55], v[58:59]
	v_pk_add_f32 v[54:55], v[56:57], 1.0 op_sel_hi:[1,0]
	v_cvt_pk_bf16_f32 v16, v16, v17
	v_pk_fma_f32 v[18:19], v[18:19], v[54:55], v[60:61]
	s_nop 0
	v_cvt_pk_bf16_f32 v17, v18, v19
	s_waitcnt lgkmcnt(0)
	v_lshl_add_u64 v[18:19], v[24:25], 1, s[14:15]
	v_lshl_add_u64 v[18:19], v[18:19], 0, v[46:47]
	v_add_co_u32_e32 v18, vcc, 0xe0c1000, v18
	s_nop 1
	v_addc_co_u32_e32 v19, vcc, 0, v19, vcc
	global_store_dwordx2 v[18:19], v[16:17], off offset:512 sc1
.LBB0_36:
	global_load_dwordx4 v[16:19], v[34:35], off offset:2048
	s_nop 0
	global_load_dwordx4 v[54:57], v[36:37], off offset:2048
	v_pk_mul_f32 v[52:53], v[52:53], v[26:27]
	v_pk_mul_f32 v[50:51], v[50:51], v[26:27]
	s_and_b64 vcc, exec, s[6:7]
	s_waitcnt vmcnt(0)
	v_pk_fma_f32 v[16:17], v[52:53], v[16:17], v[54:55]
	v_pk_fma_f32 v[18:19], v[50:51], v[18:19], v[56:57]
	s_cbranch_vccnz .LBB0_38
	v_lshl_add_u64 v[50:51], v[48:49], 0, v[148:149]
	global_store_dwordx4 v[50:51], v[16:19], off offset:2048 sc1
.LBB0_38:
	s_and_b64 vcc, exec, s[8:9]
	s_cbranch_vccnz .LBB0_40
	v_mov_b32_e32 v43, v149
	v_lshl_add_u64 v[50:51], v[30:31], 0, v[42:43]
	v_lshl_add_u64 v[54:55], v[28:29], 0, v[148:149]
	global_load_dwordx4 v[50:53], v[50:51], off
	s_nop 0
	global_load_dwordx4 v[54:57], v[54:55], off offset:2048
	s_load_dwordx2 s[14:15], s[10:11], 0x120
	v_mov_b32_e32 v47, v149
	s_waitcnt vmcnt(1)
	v_pk_add_f32 v[50:51], v[50:51], 1.0 op_sel_hi:[1,0]
	s_waitcnt vmcnt(0)
	v_pk_fma_f32 v[16:17], v[16:17], v[50:51], v[54:55]
	v_pk_add_f32 v[50:51], v[52:53], 1.0 op_sel_hi:[1,0]
	v_cvt_pk_bf16_f32 v16, v16, v17
	v_pk_fma_f32 v[18:19], v[18:19], v[50:51], v[56:57]
	s_nop 0
	v_cvt_pk_bf16_f32 v17, v18, v19
	s_waitcnt lgkmcnt(0)
	v_lshl_add_u64 v[18:19], v[24:25], 1, s[14:15]
	v_lshl_add_u64 v[18:19], v[18:19], 0, v[46:47]
	v_add_co_u32_e32 v18, vcc, 0xe0c1000, v18
	s_nop 1
	v_addc_co_u32_e32 v19, vcc, 0, v19, vcc
	global_store_dwordx2 v[18:19], v[16:17], off offset:1024 sc1
.LBB0_40:
	global_load_dwordx4 v[16:19], v[34:35], off offset:3072
	s_nop 0
	global_load_dwordx4 v[50:53], v[36:37], off offset:3072
	v_pk_mul_f32 v[22:23], v[22:23], v[26:27]
	v_pk_mul_f32 v[20:21], v[20:21], v[26:27]
	s_and_b64 vcc, exec, s[6:7]
	s_waitcnt vmcnt(0)
	v_pk_fma_f32 v[16:17], v[22:23], v[16:17], v[50:51]
	v_pk_fma_f32 v[18:19], v[20:21], v[18:19], v[52:53]
	s_cbranch_vccnz .LBB0_42
	v_lshl_add_u64 v[20:21], v[48:49], 0, v[148:149]
	global_store_dwordx4 v[20:21], v[16:19], off offset:3072 sc1
.LBB0_42:
	s_and_b64 vcc, exec, s[8:9]
	s_cbranch_vccnz .LBB0_23
	v_mov_b32_e32 v45, v149
	v_lshl_add_u64 v[20:21], v[30:31], 0, v[44:45]
	v_lshl_add_u64 v[26:27], v[28:29], 0, v[148:149]
	global_load_dwordx4 v[20:23], v[20:21], off
	s_nop 0
	global_load_dwordx4 v[26:29], v[26:27], off offset:3072
	s_load_dwordx2 s[6:7], s[10:11], 0x120
	v_mov_b32_e32 v47, v149
	s_waitcnt vmcnt(1)
	v_pk_add_f32 v[20:21], v[20:21], 1.0 op_sel_hi:[1,0]
	s_waitcnt vmcnt(0)
	v_pk_fma_f32 v[16:17], v[16:17], v[20:21], v[26:27]
	v_pk_add_f32 v[20:21], v[22:23], 1.0 op_sel_hi:[1,0]
	v_cvt_pk_bf16_f32 v16, v16, v17
	v_pk_fma_f32 v[18:19], v[18:19], v[20:21], v[28:29]
	s_nop 0
	v_cvt_pk_bf16_f32 v17, v18, v19
	s_waitcnt lgkmcnt(0)
	v_lshl_add_u64 v[18:19], v[24:25], 1, s[6:7]
	v_lshl_add_u64 v[18:19], v[18:19], 0, v[46:47]
	v_add_co_u32_e32 v18, vcc, 0xe0c1000, v18
	s_nop 1
	v_addc_co_u32_e32 v19, vcc, 0, v19, vcc
	global_store_dwordx2 v[18:19], v[16:17], off offset:1536 sc1
	s_branch .LBB0_23

.LBB0_53:
	s_cmpk_gt_i32 s84, 0x69f
	s_mov_b64 s[14:15], -1
	s_cbranch_scc0 .LBB0_83
	s_cmpk_gt_u32 s84, 0x81f
	s_cbranch_scc0 .LBB0_80
	s_cmpk_gt_u32 s84, 0x91f
	s_cbranch_scc0 .LBB0_77
	s_cmpk_gt_u32 s84, 0xd1f
	s_cbranch_scc0 .LBB0_74
	s_cmpk_gt_u32 s84, 0x111f
	s_cbranch_scc0 .LBB0_71
	s_cmpk_gt_u32 s84, 0x112f
	s_cbranch_scc0 .LBB0_68
	s_cmpk_gt_u32 s84, 0x113f
	s_cbranch_scc0 .LBB0_65
	s_cmpk_gt_u32 s84, 0x114f
	s_cbranch_scc0 .LBB0_62
	s_load_dwordx2 s[14:15], s[4:5], 0x60
	s_mov_b32 s41, s27
	s_lshl_b64 s[20:21], s[40:41], 2
	v_lshl_add_u64 v[24:25], s[40:41], 1, v[10:11]
	s_waitcnt lgkmcnt(0)
	s_add_u32 s14, s14, s20
	s_addc_u32 s15, s15, s21
	v_lshl_add_u64 v[12:13], v[8:9], 2, s[14:15]
	s_mov_b64 s[14:15], 0x40000
	v_lshl_add_u64 v[16:17], v[12:13], 0, s[14:15]
	v_add_co_u32_e32 v12, vcc, 0x40000, v12
	global_load_dwordx4 v[0:3], v[16:17], off offset:32
	global_load_dwordx4 v[4:7], v[16:17], off offset:16
	v_addc_co_u32_e32 v13, vcc, 0, v13, vcc
	global_load_dwordx4 v[12:15], v[12:13], off
	s_nop 0
	global_load_dwordx4 v[16:19], v[16:17], off offset:48
	s_mov_b64 s[14:15], 0
	s_waitcnt vmcnt(0)
	v_cvt_pk_bf16_f32 v21, v2, v3
	s_waitcnt vmcnt(2)
	v_cvt_pk_bf16_f32 v4, v4, v5
	v_cvt_pk_bf16_f32 v5, v6, v7
	s_waitcnt vmcnt(1)
	v_cvt_pk_bf16_f32 v2, v12, v13
	v_cvt_pk_bf16_f32 v3, v14, v15
	v_cvt_pk_bf16_f32 v20, v0, v1
	s_waitcnt vmcnt(0)
	v_cvt_pk_bf16_f32 v22, v16, v17
	v_cvt_pk_bf16_f32 v23, v18, v19
	global_store_dwordx4 v[24:25], v[2:5], off sc1
	global_store_dwordx4 v[24:25], v[20:23], off offset:16 sc1
.LBB0_62:
	s_andn2_b64 vcc, exec, s[14:15]
	s_cbranch_vccnz .LBB0_64
	s_add_i32 s20, s84, 0xffffeec0
	s_cmp_gt_u32 s20, 7
	s_cselect_b32 s2, 64, 0
	s_add_i32 s21, s84, 0xffffeeb8
	s_load_dwordx2 s[14:15], s[4:5], 0xc0
	s_cmp_lt_u32 s20, 8
	s_cselect_b32 s20, s20, s21
	s_lshl_b32 s20, s20, 6
	s_ashr_i32 s21, s20, 31
	v_mov_b32_e32 v14, v254
	s_lshl_b64 s[86:87], s[20:21], 2
	s_waitcnt lgkmcnt(0)
	s_add_u32 s14, s14, s86
	v_ashrrev_i32_e32 v2, 4, v14
	v_lshlrev_b32_e32 v15, 4, v14
	s_addc_u32 s15, s15, s87
	v_and_b32_e32 v148, 0xf0, v15
	v_add_u32_e32 v6, s2, v2
	v_lshl_add_u64 v[0:1], s[14:15], 0, v[148:149]
	s_mov_b64 s[14:15], 0x40000
	v_ashrrev_i32_e32 v7, 31, v6
	v_lshl_add_u64 v[4:5], v[0:1], 0, s[14:15]
	v_lshlrev_b64 v[0:1], 11, v[6:7]
	v_lshl_add_u64 v[0:1], v[4:5], 0, v[0:1]
	s_barrier
	v_mad_u64_u32 v[12:13], s[14:15], v2, s93, v[148:149]
	global_load_dwordx4 v[0:3], v[0:1], off
	v_add_u32_e32 v7, 0x1040, v12
	v_and_b32_e32 v21, 48, v15
	v_ashrrev_i32_e32 v20, 2, v14
	s_lshl_b32 s26, s2, 1
	v_lshlrev_b32_e32 v148, 1, v21
	s_waitcnt vmcnt(0)
	ds_write2_b32 v12, v0, v1 offset1:1
	ds_write2_b32 v12, v2, v3 offset0:2 offset1:3
	v_add_u32_e32 v0, 16, v6
	v_ashrrev_i32_e32 v1, 31, v0
	v_lshlrev_b64 v[0:1], 11, v[0:1]
	v_lshl_add_u64 v[0:1], v[4:5], 0, v[0:1]
	global_load_dwordx4 v[0:3], v[0:1], off
	s_waitcnt vmcnt(0)
	ds_write2_b32 v7, v0, v1 offset1:1
	v_add_u32_e32 v0, 0x1048, v12
	ds_write2_b32 v0, v2, v3 offset1:1
	v_add_u32_e32 v0, 32, v6
	v_ashrrev_i32_e32 v1, 31, v0
	v_lshlrev_b64 v[0:1], 11, v[0:1]
	v_lshl_add_u64 v[0:1], v[4:5], 0, v[0:1]
	global_load_dwordx4 v[0:3], v[0:1], off
	v_add_u32_e32 v7, 0x2080, v12
	s_waitcnt vmcnt(0)
	ds_write2_b32 v7, v0, v1 offset1:1
	v_add_u32_e32 v0, 0x2088, v12
	ds_write2_b32 v0, v2, v3 offset1:1
	v_add_u32_e32 v0, 48, v6
	v_ashrrev_i32_e32 v1, 31, v0
	v_lshlrev_b64 v[0:1], 11, v[0:1]
	v_lshl_add_u64 v[0:1], v[4:5], 0, v[0:1]
	global_load_dwordx4 v[0:3], v[0:1], off
	v_add_u32_e32 v4, 0x30c0, v12
	s_waitcnt vmcnt(0)
	ds_write2_b32 v4, v0, v1 offset1:1
	v_add_u32_e32 v0, 0x30c8, v12
	ds_write2_b32 v0, v2, v3 offset1:1
	v_and_b32_e32 v0, -4, v14
	v_mul_u32_u24_e32 v1, 0x41, v21
	v_lshl_add_u32 v2, v1, 2, v0
	s_waitcnt lgkmcnt(0)
	s_barrier
	ds_read2_b32 v[4:5], v2 offset1:65
	v_add_u32_e32 v3, 0x800, v2
	ds_read2_b32 v[12:13], v3 offset0:8 offset1:73
	ds_read2_b32 v[0:1], v2 offset0:130 offset1:195
	ds_read2_b32 v[14:15], v3 offset0:138 offset1:203
	v_add_u32_e32 v3, 0x400, v2
	ds_read2_b32 v[6:7], v3 offset0:4 offset1:69
	v_add_u32_e32 v18, 0xc00, v2
	s_waitcnt lgkmcnt(2)
	v_cvt_pk_bf16_f32 v1, v0, v1
	v_cvt_pk_bf16_f32 v0, v4, v5
	v_cvt_pk_bf16_f32 v4, v12, v13
	v_add_u32_e32 v12, s20, v20
	ds_read2_b32 v[16:17], v18 offset0:12 offset1:77
	ds_read2_b32 v[2:3], v3 offset0:134 offset1:199
	ds_read2_b32 v[18:19], v18 offset0:142 offset1:207
	v_ashrrev_i32_e32 v13, 31, v12
	v_lshlrev_b64 v[12:13], 8, v[12:13]
	v_lshl_add_u64 v[12:13], s[10:11], 0, v[12:13]
	v_lshl_add_u64 v[12:13], v[12:13], 0, s[26:27]
	s_waitcnt lgkmcnt(1)
	v_cvt_pk_bf16_f32 v3, v2, v3
	v_cvt_pk_bf16_f32 v2, v6, v7
	v_lshl_add_u64 v[12:13], v[12:13], 0, v[148:149]
	s_waitcnt lgkmcnt(0)
	v_cvt_pk_bf16_f32 v7, v18, v19
	v_cvt_pk_bf16_f32 v6, v16, v17
	v_cvt_pk_bf16_f32 v5, v14, v15
	global_store_dwordx4 v[12:13], v[0:3], off sc1
	global_store_dwordx4 v[12:13], v[4:7], off offset:16 sc1

.LBB0_65:
	s_andn2_b64 vcc, exec, s[14:15]
	s_cbranch_vccnz .LBB0_67
	s_load_dwordx2 s[20:21], s[4:5], 0xa0
	s_add_i32 s2, s84, 0xffffeed0
	s_lshr_b32 s14, s2, 3
	s_add_i32 s26, s14, 2
	s_lshl_b64 s[86:87], s[26:27], 17
	s_waitcnt lgkmcnt(0)
	s_add_u32 s25, s20, s86
	s_mov_b32 s15, s27
	s_addc_u32 s26, s21, s87
	s_lshl_b64 s[14:15], s[14:15], 16
	s_add_u32 s20, s16, s14
	s_addc_u32 s21, s17, s15
	s_and_b32 s2, s45, 0x1c0
	v_mov_b32_e32 v12, v254
	s_lshl_b32 s14, s2, 2
	s_add_u32 s14, s25, s14
	v_ashrrev_i32_e32 v0, 4, v12
	v_lshlrev_b32_e32 v13, 4, v12
	s_addc_u32 s15, s26, 0
	v_and_b32_e32 v148, 0xf0, v13
	v_ashrrev_i32_e32 v1, 31, v0
	v_lshl_add_u64 v[2:3], s[14:15], 0, v[148:149]
	v_lshlrev_b64 v[4:5], 11, v[0:1]
	v_lshl_add_u64 v[4:5], v[2:3], 0, v[4:5]
	s_barrier
	v_mad_u64_u32 v[6:7], s[14:15], v0, s93, v[148:149]
	global_load_dwordx4 v[0:3], v[4:5], off
	s_mov_b32 s14, 0x8000
	v_add_u32_e32 v7, 0x1040, v6
	v_and_b32_e32 v21, 48, v13
	v_ashrrev_i32_e32 v20, 2, v12
	v_lshlrev_b32_e32 v148, 1, v21
	s_waitcnt vmcnt(0)
	ds_write2_b32 v6, v0, v1 offset1:1
	ds_write2_b32 v6, v2, v3 offset0:2 offset1:3
	v_add_co_u32_e32 v0, vcc, s14, v4
	s_mov_b32 s14, 0x10000
	s_nop 0
	v_addc_co_u32_e32 v1, vcc, 0, v5, vcc
	global_load_dwordx4 v[0:3], v[0:1], off
	s_waitcnt vmcnt(0)
	ds_write2_b32 v7, v0, v1 offset1:1
	v_add_u32_e32 v0, 0x1048, v6
	ds_write2_b32 v0, v2, v3 offset1:1
	v_add_co_u32_e32 v0, vcc, s14, v4
	v_add_u32_e32 v7, 0x2080, v6
	s_nop 0
	v_addc_co_u32_e32 v1, vcc, 0, v5, vcc
	global_load_dwordx4 v[0:3], v[0:1], off
	s_mov_b32 s14, 0x18000
	s_waitcnt vmcnt(0)
	ds_write2_b32 v7, v0, v1 offset1:1
	v_add_u32_e32 v0, 0x2088, v6
	ds_write2_b32 v0, v2, v3 offset1:1
	v_add_co_u32_e32 v0, vcc, s14, v4
	v_add_u32_e32 v7, 0x30c0, v6
	s_nop 0
	v_addc_co_u32_e32 v1, vcc, 0, v5, vcc
	global_load_dwordx4 v[0:3], v[0:1], off
	s_waitcnt vmcnt(0)
	ds_write2_b32 v7, v0, v1 offset1:1
	v_add_u32_e32 v0, 0x30c8, v6
	ds_write2_b32 v0, v2, v3 offset1:1
	v_and_b32_e32 v0, -4, v12
	v_mul_u32_u24_e32 v1, 0x41, v21
	v_lshl_add_u32 v2, v1, 2, v0
	s_waitcnt lgkmcnt(0)
	s_barrier
	ds_read2_b32 v[4:5], v2 offset1:65
	v_add_u32_e32 v3, 0x800, v2
	ds_read2_b32 v[12:13], v3 offset0:8 offset1:73
	ds_read2_b32 v[0:1], v2 offset0:130 offset1:195
	ds_read2_b32 v[14:15], v3 offset0:138 offset1:203
	v_add_u32_e32 v3, 0x400, v2
	ds_read2_b32 v[6:7], v3 offset0:4 offset1:69
	v_add_u32_e32 v18, 0xc00, v2
	ds_read2_b32 v[16:17], v18 offset0:12 offset1:77
	ds_read2_b32 v[2:3], v3 offset0:134 offset1:199
	ds_read2_b32 v[18:19], v18 offset0:142 offset1:207
	s_waitcnt lgkmcnt(5)
	v_cvt_pk_bf16_f32 v1, v0, v1
	v_cvt_pk_bf16_f32 v0, v4, v5
	v_cvt_pk_bf16_f32 v4, v12, v13
	v_add_u32_e32 v12, s2, v20
	v_ashrrev_i32_e32 v13, 31, v12
	v_lshlrev_b64 v[12:13], 7, v[12:13]
	v_lshl_add_u64 v[12:13], s[20:21], 0, v[12:13]
	s_waitcnt lgkmcnt(1)
	v_cvt_pk_bf16_f32 v3, v2, v3
	v_cvt_pk_bf16_f32 v2, v6, v7
	v_lshl_add_u64 v[12:13], v[12:13], 0, v[148:149]
	s_waitcnt lgkmcnt(0)
	v_cvt_pk_bf16_f32 v7, v18, v19
	v_cvt_pk_bf16_f32 v6, v16, v17
	v_cvt_pk_bf16_f32 v5, v14, v15
	global_store_dwordx4 v[12:13], v[0:3], off sc1
	global_store_dwordx4 v[12:13], v[4:7], off offset:16 sc1

.LBB0_68:
	s_andn2_b64 vcc, exec, s[14:15]
	s_cbranch_vccnz .LBB0_70
	s_load_dwordx2 s[20:21], s[4:5], 0x90
	s_add_i32 s2, s84, 0xffffeee0
	s_lshr_b32 s14, s2, 3
	s_add_i32 s26, s14, 2
	s_lshl_b64 s[86:87], s[26:27], 17
	s_waitcnt lgkmcnt(0)
	s_add_u32 s25, s20, s86
	s_mov_b32 s15, s27
	s_addc_u32 s26, s21, s87
	s_lshl_b64 s[14:15], s[14:15], 16
	s_add_u32 s20, s22, s14
	s_addc_u32 s21, s23, s15
	s_and_b32 s2, s45, 0x1c0
	v_mov_b32_e32 v12, v254
	s_lshl_b32 s14, s2, 2
	s_add_u32 s14, s25, s14
	v_ashrrev_i32_e32 v0, 4, v12
	v_lshlrev_b32_e32 v13, 4, v12
	s_addc_u32 s15, s26, 0
	v_and_b32_e32 v148, 0xf0, v13
	v_ashrrev_i32_e32 v1, 31, v0
	v_lshl_add_u64 v[2:3], s[14:15], 0, v[148:149]
	v_lshlrev_b64 v[4:5], 11, v[0:1]
	v_lshl_add_u64 v[4:5], v[2:3], 0, v[4:5]
	s_barrier
	v_mad_u64_u32 v[6:7], s[14:15], v0, s93, v[148:149]
	global_load_dwordx4 v[0:3], v[4:5], off
	s_mov_b32 s14, 0x8000
	v_add_u32_e32 v7, 0x1040, v6
	v_and_b32_e32 v21, 48, v13
	v_ashrrev_i32_e32 v20, 2, v12
	v_lshlrev_b32_e32 v148, 1, v21
	s_waitcnt vmcnt(0)
	ds_write2_b32 v6, v0, v1 offset1:1
	ds_write2_b32 v6, v2, v3 offset0:2 offset1:3
	v_add_co_u32_e32 v0, vcc, s14, v4
	s_mov_b32 s14, 0x10000
	s_nop 0
	v_addc_co_u32_e32 v1, vcc, 0, v5, vcc
	global_load_dwordx4 v[0:3], v[0:1], off
	s_waitcnt vmcnt(0)
	ds_write2_b32 v7, v0, v1 offset1:1
	v_add_u32_e32 v0, 0x1048, v6
	ds_write2_b32 v0, v2, v3 offset1:1
	v_add_co_u32_e32 v0, vcc, s14, v4
	v_add_u32_e32 v7, 0x2080, v6
	s_nop 0
	v_addc_co_u32_e32 v1, vcc, 0, v5, vcc
	global_load_dwordx4 v[0:3], v[0:1], off
	s_mov_b32 s14, 0x18000
	s_waitcnt vmcnt(0)
	ds_write2_b32 v7, v0, v1 offset1:1
	v_add_u32_e32 v0, 0x2088, v6
	ds_write2_b32 v0, v2, v3 offset1:1
	v_add_co_u32_e32 v0, vcc, s14, v4
	v_add_u32_e32 v7, 0x30c0, v6
	s_nop 0
	v_addc_co_u32_e32 v1, vcc, 0, v5, vcc
	global_load_dwordx4 v[0:3], v[0:1], off
	s_waitcnt vmcnt(0)
	ds_write2_b32 v7, v0, v1 offset1:1
	v_add_u32_e32 v0, 0x30c8, v6
	ds_write2_b32 v0, v2, v3 offset1:1
	v_and_b32_e32 v0, -4, v12
	v_mul_u32_u24_e32 v1, 0x41, v21
	v_lshl_add_u32 v2, v1, 2, v0
	s_waitcnt lgkmcnt(0)
	s_barrier
	ds_read2_b32 v[4:5], v2 offset1:65
	v_add_u32_e32 v3, 0x800, v2
	ds_read2_b32 v[12:13], v3 offset0:8 offset1:73
	ds_read2_b32 v[0:1], v2 offset0:130 offset1:195
	ds_read2_b32 v[14:15], v3 offset0:138 offset1:203
	v_add_u32_e32 v3, 0x400, v2
	ds_read2_b32 v[6:7], v3 offset0:4 offset1:69
	v_add_u32_e32 v18, 0xc00, v2
	ds_read2_b32 v[16:17], v18 offset0:12 offset1:77
	ds_read2_b32 v[2:3], v3 offset0:134 offset1:199
	ds_read2_b32 v[18:19], v18 offset0:142 offset1:207
	s_waitcnt lgkmcnt(5)
	v_cvt_pk_bf16_f32 v1, v0, v1
	v_cvt_pk_bf16_f32 v0, v4, v5
	v_cvt_pk_bf16_f32 v4, v12, v13
	v_add_u32_e32 v12, s2, v20
	v_ashrrev_i32_e32 v13, 31, v12
	v_lshlrev_b64 v[12:13], 7, v[12:13]
	v_lshl_add_u64 v[12:13], s[20:21], 0, v[12:13]
	s_waitcnt lgkmcnt(1)
	v_cvt_pk_bf16_f32 v3, v2, v3
	v_cvt_pk_bf16_f32 v2, v6, v7
	v_lshl_add_u64 v[12:13], v[12:13], 0, v[148:149]
	s_waitcnt lgkmcnt(0)
	v_cvt_pk_bf16_f32 v7, v18, v19
	v_cvt_pk_bf16_f32 v6, v16, v17
	v_cvt_pk_bf16_f32 v5, v14, v15
	global_store_dwordx4 v[12:13], v[0:3], off sc1
	global_store_dwordx4 v[12:13], v[4:7], off offset:16 sc1

.LBB0_71:
	s_andn2_b64 vcc, exec, s[14:15]
	s_cbranch_vccnz .LBB0_73
	s_load_dwordx2 s[20:21], s[4:5], 0x100
	s_and_b32 s14, s45, 0x3c0
	s_and_b32 s2, s44, 0x3ffc0
	v_mov_b32_e32 v14, v254
	s_lshl_b32 s15, s14, 2
	s_waitcnt lgkmcnt(0)
	s_add_u32 s20, s20, s15
	v_ashrrev_i32_e32 v2, 4, v14
	v_lshlrev_b32_e32 v15, 4, v14
	s_addc_u32 s21, s21, 0
	v_and_b32_e32 v148, 0xf0, v15
	v_add_u32_e32 v6, s2, v2
	v_lshl_add_u64 v[0:1], s[20:21], 0, v[148:149]
	s_mov_b64 s[20:21], 0x1000000
	v_ashrrev_i32_e32 v7, 31, v6
	v_lshl_add_u64 v[4:5], v[0:1], 0, s[20:21]
	v_lshlrev_b64 v[0:1], 12, v[6:7]
	v_lshl_add_u64 v[0:1], v[4:5], 0, v[0:1]
	s_barrier
	v_mad_u64_u32 v[12:13], s[20:21], v2, s93, v[148:149]
	global_load_dwordx4 v[0:3], v[0:1], off
	v_add_u32_e32 v7, 0x1040, v12
	v_and_b32_e32 v21, 48, v15
	v_ashrrev_i32_e32 v20, 2, v14
	s_lshl_b32 s26, s2, 1
	v_lshlrev_b32_e32 v148, 1, v21
	s_waitcnt vmcnt(0)
	ds_write2_b32 v12, v0, v1 offset1:1
	ds_write2_b32 v12, v2, v3 offset0:2 offset1:3
	v_add_u32_e32 v0, 16, v6
	v_ashrrev_i32_e32 v1, 31, v0
	v_lshlrev_b64 v[0:1], 12, v[0:1]
	v_lshl_add_u64 v[0:1], v[4:5], 0, v[0:1]
	global_load_dwordx4 v[0:3], v[0:1], off
	s_waitcnt vmcnt(0)
	ds_write2_b32 v7, v0, v1 offset1:1
	v_add_u32_e32 v0, 0x1048, v12
	ds_write2_b32 v0, v2, v3 offset1:1
	v_add_u32_e32 v0, 32, v6
	v_ashrrev_i32_e32 v1, 31, v0
	v_lshlrev_b64 v[0:1], 12, v[0:1]
	v_lshl_add_u64 v[0:1], v[4:5], 0, v[0:1]
	global_load_dwordx4 v[0:3], v[0:1], off
	v_add_u32_e32 v7, 0x2080, v12
	s_waitcnt vmcnt(0)
	ds_write2_b32 v7, v0, v1 offset1:1
	v_add_u32_e32 v0, 0x2088, v12
	ds_write2_b32 v0, v2, v3 offset1:1
	v_add_u32_e32 v0, 48, v6
	v_ashrrev_i32_e32 v1, 31, v0
	v_lshlrev_b64 v[0:1], 12, v[0:1]
	v_lshl_add_u64 v[0:1], v[4:5], 0, v[0:1]
	global_load_dwordx4 v[0:3], v[0:1], off
	v_add_u32_e32 v4, 0x30c0, v12
	s_waitcnt vmcnt(0)
	ds_write2_b32 v4, v0, v1 offset1:1
	v_add_u32_e32 v0, 0x30c8, v12
	ds_write2_b32 v0, v2, v3 offset1:1
	v_and_b32_e32 v0, -4, v14
	v_mul_u32_u24_e32 v1, 0x41, v21
	v_lshl_add_u32 v2, v1, 2, v0
	s_waitcnt lgkmcnt(0)
	s_barrier
	ds_read2_b32 v[4:5], v2 offset1:65
	v_add_u32_e32 v3, 0x800, v2
	ds_read2_b32 v[12:13], v3 offset0:8 offset1:73
	ds_read2_b32 v[0:1], v2 offset0:130 offset1:195
	ds_read2_b32 v[14:15], v3 offset0:138 offset1:203
	v_add_u32_e32 v3, 0x400, v2
	ds_read2_b32 v[6:7], v3 offset0:4 offset1:69
	v_add_u32_e32 v18, 0xc00, v2
	s_waitcnt lgkmcnt(2)
	v_cvt_pk_bf16_f32 v1, v0, v1
	v_cvt_pk_bf16_f32 v0, v4, v5
	v_cvt_pk_bf16_f32 v4, v12, v13
	v_add_u32_e32 v12, s14, v20
	ds_read2_b32 v[16:17], v18 offset0:12 offset1:77
	ds_read2_b32 v[2:3], v3 offset0:134 offset1:199
	ds_read2_b32 v[18:19], v18 offset0:142 offset1:207
	v_ashrrev_i32_e32 v13, 31, v12
	v_lshlrev_b64 v[12:13], 13, v[12:13]
	v_lshl_add_u64 v[12:13], s[12:13], 0, v[12:13]
	v_lshl_add_u64 v[12:13], v[12:13], 0, s[26:27]
	s_waitcnt lgkmcnt(1)
	v_cvt_pk_bf16_f32 v3, v2, v3
	v_cvt_pk_bf16_f32 v2, v6, v7
	v_lshl_add_u64 v[12:13], v[12:13], 0, v[148:149]
	s_waitcnt lgkmcnt(0)
	v_cvt_pk_bf16_f32 v7, v18, v19
	v_cvt_pk_bf16_f32 v6, v16, v17
	v_cvt_pk_bf16_f32 v5, v14, v15
	global_store_dwordx4 v[12:13], v[0:3], off sc1
	global_store_dwordx4 v[12:13], v[4:7], off offset:16 sc1

.LBB0_74:
	s_andn2_b64 vcc, exec, s[14:15]
	s_cbranch_vccnz .LBB0_76
	s_load_dwordx2 s[20:21], s[4:5], 0xf8
	s_add_i32 s14, s45, 0xfffdb800
	s_add_i32 s2, s84, 0xfffff6e0
	s_and_b32 s14, s14, 0xfc0
	s_and_b32 s2, s2, 0xffc0
	v_mov_b32_e32 v14, v254
	s_lshl_b32 s15, s14, 2
	s_waitcnt lgkmcnt(0)
	s_add_u32 s20, s20, s15
	v_ashrrev_i32_e32 v2, 4, v14
	v_lshlrev_b32_e32 v15, 4, v14
	s_addc_u32 s21, s21, 0
	v_and_b32_e32 v148, 0xf0, v15
	v_add_u32_e32 v6, s2, v2
	v_lshl_add_u64 v[0:1], s[20:21], 0, v[148:149]
	s_mov_b64 s[20:21], 0x1000000
	v_ashrrev_i32_e32 v7, 31, v6
	v_lshl_add_u64 v[4:5], v[0:1], 0, s[20:21]
	v_lshlrev_b64 v[0:1], 14, v[6:7]
	v_lshl_add_u64 v[0:1], v[4:5], 0, v[0:1]
	s_barrier
	v_mad_u64_u32 v[12:13], s[20:21], v2, s93, v[148:149]
	global_load_dwordx4 v[0:3], v[0:1], off
	v_add_u32_e32 v7, 0x1040, v12
	v_and_b32_e32 v21, 48, v15
	v_ashrrev_i32_e32 v20, 2, v14
	s_lshl_b32 s26, s2, 1
	v_lshlrev_b32_e32 v148, 1, v21
	s_waitcnt vmcnt(0)
	ds_write2_b32 v12, v0, v1 offset1:1
	ds_write2_b32 v12, v2, v3 offset0:2 offset1:3
	v_add_u32_e32 v0, 16, v6
	v_ashrrev_i32_e32 v1, 31, v0
	v_lshlrev_b64 v[0:1], 14, v[0:1]
	v_lshl_add_u64 v[0:1], v[4:5], 0, v[0:1]
	global_load_dwordx4 v[0:3], v[0:1], off
	s_waitcnt vmcnt(0)
	ds_write2_b32 v7, v0, v1 offset1:1
	v_add_u32_e32 v0, 0x1048, v12
	ds_write2_b32 v0, v2, v3 offset1:1
	v_add_u32_e32 v0, 32, v6
	v_ashrrev_i32_e32 v1, 31, v0
	v_lshlrev_b64 v[0:1], 14, v[0:1]
	v_lshl_add_u64 v[0:1], v[4:5], 0, v[0:1]
	global_load_dwordx4 v[0:3], v[0:1], off
	v_add_u32_e32 v7, 0x2080, v12
	s_waitcnt vmcnt(0)
	ds_write2_b32 v7, v0, v1 offset1:1
	v_add_u32_e32 v0, 0x2088, v12
	ds_write2_b32 v0, v2, v3 offset1:1
	v_add_u32_e32 v0, 48, v6
	v_ashrrev_i32_e32 v1, 31, v0
	v_lshlrev_b64 v[0:1], 14, v[0:1]
	v_lshl_add_u64 v[0:1], v[4:5], 0, v[0:1]
	global_load_dwordx4 v[0:3], v[0:1], off
	v_add_u32_e32 v4, 0x30c0, v12
	s_waitcnt vmcnt(0)
	ds_write2_b32 v4, v0, v1 offset1:1
	v_add_u32_e32 v0, 0x30c8, v12
	ds_write2_b32 v0, v2, v3 offset1:1
	v_and_b32_e32 v0, -4, v14
	v_mul_u32_u24_e32 v1, 0x41, v21
	v_lshl_add_u32 v2, v1, 2, v0
	s_waitcnt lgkmcnt(0)
	s_barrier
	ds_read2_b32 v[4:5], v2 offset1:65
	v_add_u32_e32 v3, 0x800, v2
	ds_read2_b32 v[12:13], v3 offset0:8 offset1:73
	ds_read2_b32 v[0:1], v2 offset0:130 offset1:195
	ds_read2_b32 v[14:15], v3 offset0:138 offset1:203
	v_add_u32_e32 v3, 0x400, v2
	ds_read2_b32 v[6:7], v3 offset0:4 offset1:69
	v_add_u32_e32 v18, 0xc00, v2
	s_waitcnt lgkmcnt(2)
	v_cvt_pk_bf16_f32 v1, v0, v1
	v_cvt_pk_bf16_f32 v0, v4, v5
	v_cvt_pk_bf16_f32 v4, v12, v13
	v_add_u32_e32 v12, s14, v20
	ds_read2_b32 v[16:17], v18 offset0:12 offset1:77
	ds_read2_b32 v[2:3], v3 offset0:134 offset1:199
	ds_read2_b32 v[18:19], v18 offset0:142 offset1:207
	v_ashrrev_i32_e32 v13, 31, v12
	v_lshlrev_b64 v[12:13], 11, v[12:13]
	v_lshl_add_u64 v[12:13], s[8:9], 0, v[12:13]
	v_lshl_add_u64 v[12:13], v[12:13], 0, s[26:27]
	s_waitcnt lgkmcnt(1)
	v_cvt_pk_bf16_f32 v3, v2, v3
	v_cvt_pk_bf16_f32 v2, v6, v7
	v_lshl_add_u64 v[12:13], v[12:13], 0, v[148:149]
	s_waitcnt lgkmcnt(0)
	v_cvt_pk_bf16_f32 v7, v18, v19
	v_cvt_pk_bf16_f32 v6, v16, v17
	v_cvt_pk_bf16_f32 v5, v14, v15
	global_store_dwordx4 v[12:13], v[0:3], off sc1
	global_store_dwordx4 v[12:13], v[4:7], off offset:16 sc1

.LBB0_77:
	s_andn2_b64 vcc, exec, s[14:15]
	s_cbranch_vccnz .LBB0_79
	s_load_dwordx2 s[20:21], s[4:5], 0xe0
	s_add_i32 s2, s44, 0xfffc3800
	s_and_b32 s14, s45, 0x3c0
	s_and_b32 s2, s2, 0x3c0
	v_mov_b32_e32 v14, v254
	s_lshl_b32 s15, s14, 2
	s_waitcnt lgkmcnt(0)
	s_add_u32 s20, s20, s15
	v_ashrrev_i32_e32 v2, 4, v14
	v_lshlrev_b32_e32 v15, 4, v14
	s_addc_u32 s21, s21, 0
	v_and_b32_e32 v148, 0xf0, v15
	v_add_u32_e32 v6, s2, v2
	v_lshl_add_u64 v[0:1], s[20:21], 0, v[148:149]
	s_mov_b64 s[20:21], 0x400000
	v_ashrrev_i32_e32 v7, 31, v6
	v_lshl_add_u64 v[4:5], v[0:1], 0, s[20:21]
	v_lshlrev_b64 v[0:1], 12, v[6:7]
	v_lshl_add_u64 v[0:1], v[4:5], 0, v[0:1]
	s_barrier
	v_mad_u64_u32 v[12:13], s[20:21], v2, s93, v[148:149]
	global_load_dwordx4 v[0:3], v[0:1], off
	v_add_u32_e32 v7, 0x1040, v12
	v_and_b32_e32 v21, 48, v15
	v_ashrrev_i32_e32 v20, 2, v14
	s_lshl_b32 s26, s2, 1
	v_lshlrev_b32_e32 v148, 1, v21
	s_waitcnt vmcnt(0)
	ds_write2_b32 v12, v0, v1 offset1:1
	ds_write2_b32 v12, v2, v3 offset0:2 offset1:3
	v_add_u32_e32 v0, 16, v6
	v_ashrrev_i32_e32 v1, 31, v0
	v_lshlrev_b64 v[0:1], 12, v[0:1]
	v_lshl_add_u64 v[0:1], v[4:5], 0, v[0:1]
	global_load_dwordx4 v[0:3], v[0:1], off
	s_waitcnt vmcnt(0)
	ds_write2_b32 v7, v0, v1 offset1:1
	v_add_u32_e32 v0, 0x1048, v12
	ds_write2_b32 v0, v2, v3 offset1:1
	v_add_u32_e32 v0, 32, v6
	v_ashrrev_i32_e32 v1, 31, v0
	v_lshlrev_b64 v[0:1], 12, v[0:1]
	v_lshl_add_u64 v[0:1], v[4:5], 0, v[0:1]
	global_load_dwordx4 v[0:3], v[0:1], off
	v_add_u32_e32 v7, 0x2080, v12
	s_waitcnt vmcnt(0)
	ds_write2_b32 v7, v0, v1 offset1:1
	v_add_u32_e32 v0, 0x2088, v12
	ds_write2_b32 v0, v2, v3 offset1:1
	v_add_u32_e32 v0, 48, v6
	v_ashrrev_i32_e32 v1, 31, v0
	v_lshlrev_b64 v[0:1], 12, v[0:1]
	v_lshl_add_u64 v[0:1], v[4:5], 0, v[0:1]
	global_load_dwordx4 v[0:3], v[0:1], off
	v_add_u32_e32 v4, 0x30c0, v12
	s_waitcnt vmcnt(0)
	ds_write2_b32 v4, v0, v1 offset1:1
	v_add_u32_e32 v0, 0x30c8, v12
	ds_write2_b32 v0, v2, v3 offset1:1
	v_and_b32_e32 v0, -4, v14
	v_mul_u32_u24_e32 v1, 0x41, v21
	v_lshl_add_u32 v2, v1, 2, v0
	s_waitcnt lgkmcnt(0)
	s_barrier
	ds_read2_b32 v[4:5], v2 offset1:65
	v_add_u32_e32 v3, 0x800, v2
	ds_read2_b32 v[12:13], v3 offset0:8 offset1:73
	ds_read2_b32 v[0:1], v2 offset0:130 offset1:195
	ds_read2_b32 v[14:15], v3 offset0:138 offset1:203
	v_add_u32_e32 v3, 0x400, v2
	ds_read2_b32 v[6:7], v3 offset0:4 offset1:69
	v_add_u32_e32 v18, 0xc00, v2
	s_waitcnt lgkmcnt(2)
	v_cvt_pk_bf16_f32 v1, v0, v1
	v_cvt_pk_bf16_f32 v0, v4, v5
	v_cvt_pk_bf16_f32 v4, v12, v13
	v_add_u32_e32 v12, s14, v20
	ds_read2_b32 v[16:17], v18 offset0:12 offset1:77
	ds_read2_b32 v[2:3], v3 offset0:134 offset1:199
	ds_read2_b32 v[18:19], v18 offset0:142 offset1:207
	v_ashrrev_i32_e32 v13, 31, v12
	v_lshlrev_b64 v[12:13], 11, v[12:13]
	v_lshl_add_u64 v[12:13], s[28:29], 0, v[12:13]
	v_lshl_add_u64 v[12:13], v[12:13], 0, s[26:27]
	s_waitcnt lgkmcnt(1)
	v_cvt_pk_bf16_f32 v3, v2, v3
	v_cvt_pk_bf16_f32 v2, v6, v7
	v_lshl_add_u64 v[12:13], v[12:13], 0, v[148:149]
	s_waitcnt lgkmcnt(0)
	v_cvt_pk_bf16_f32 v7, v18, v19
	v_cvt_pk_bf16_f32 v6, v16, v17
	v_cvt_pk_bf16_f32 v5, v14, v15
	global_store_dwordx4 v[12:13], v[0:3], off sc1
	global_store_dwordx4 v[12:13], v[4:7], off offset:16 sc1

.LBB0_80:
	s_andn2_b64 vcc, exec, s[14:15]
	s_cbranch_vccnz .LBB0_82
	s_load_dwordx2 s[20:21], s[4:5], 0xd8
	s_add_i32 s2, s84, 0xfffff960
	s_lshr_b32 s14, s2, 7
	s_add_i32 s26, s14, 3
	s_lshl_b64 s[86:87], s[26:27], 21
	s_waitcnt lgkmcnt(0)
	s_add_u32 s25, s20, s86
	s_mov_b32 s15, s27
	s_addc_u32 s26, s21, s87
	s_lshl_b64 s[14:15], s[14:15], 20
	s_add_u32 s20, s36, s14
	s_addc_u32 s21, s37, s15
	s_add_i32 s2, s44, 0xfffc1a00
	s_and_b32 s14, s45, 0x3c0
	v_mov_b32_e32 v14, v254
	s_and_b32 s2, s2, 0x1c0
	s_lshl_b32 s15, s14, 2
	v_ashrrev_i32_e32 v2, 4, v14
	s_add_u32 s86, s25, s15
	v_lshlrev_b32_e32 v15, 4, v14
	v_add_u32_e32 v6, s2, v2
	s_addc_u32 s87, s26, 0
	v_and_b32_e32 v148, 0xf0, v15
	v_ashrrev_i32_e32 v7, 31, v6
	v_lshl_add_u64 v[4:5], s[86:87], 0, v[148:149]
	v_lshlrev_b64 v[0:1], 12, v[6:7]
	v_lshl_add_u64 v[0:1], v[4:5], 0, v[0:1]
	s_barrier
	v_mad_u64_u32 v[12:13], s[86:87], v2, s93, v[148:149]
	global_load_dwordx4 v[0:3], v[0:1], off
	v_add_u32_e32 v7, 0x1040, v12
	v_and_b32_e32 v21, 48, v15
	v_ashrrev_i32_e32 v20, 2, v14
	s_lshl_b32 s26, s2, 1
	v_lshlrev_b32_e32 v148, 1, v21
	s_waitcnt vmcnt(0)
	ds_write2_b32 v12, v0, v1 offset1:1
	ds_write2_b32 v12, v2, v3 offset0:2 offset1:3
	v_add_u32_e32 v0, 16, v6
	v_ashrrev_i32_e32 v1, 31, v0
	v_lshlrev_b64 v[0:1], 12, v[0:1]
	v_lshl_add_u64 v[0:1], v[4:5], 0, v[0:1]
	global_load_dwordx4 v[0:3], v[0:1], off
	s_waitcnt vmcnt(0)
	ds_write2_b32 v7, v0, v1 offset1:1
	v_add_u32_e32 v0, 0x1048, v12
	ds_write2_b32 v0, v2, v3 offset1:1
	v_add_u32_e32 v0, 32, v6
	v_ashrrev_i32_e32 v1, 31, v0
	v_lshlrev_b64 v[0:1], 12, v[0:1]
	v_lshl_add_u64 v[0:1], v[4:5], 0, v[0:1]
	global_load_dwordx4 v[0:3], v[0:1], off
	v_add_u32_e32 v7, 0x2080, v12
	s_waitcnt vmcnt(0)
	ds_write2_b32 v7, v0, v1 offset1:1
	v_add_u32_e32 v0, 0x2088, v12
	ds_write2_b32 v0, v2, v3 offset1:1
	v_add_u32_e32 v0, 48, v6
	v_ashrrev_i32_e32 v1, 31, v0
	v_lshlrev_b64 v[0:1], 12, v[0:1]
	v_lshl_add_u64 v[0:1], v[4:5], 0, v[0:1]
	global_load_dwordx4 v[0:3], v[0:1], off
	v_add_u32_e32 v4, 0x30c0, v12
	s_waitcnt vmcnt(0)
	ds_write2_b32 v4, v0, v1 offset1:1
	v_add_u32_e32 v0, 0x30c8, v12
	ds_write2_b32 v0, v2, v3 offset1:1
	v_and_b32_e32 v0, -4, v14
	v_mul_u32_u24_e32 v1, 0x41, v21
	v_lshl_add_u32 v2, v1, 2, v0
	s_waitcnt lgkmcnt(0)
	s_barrier
	ds_read2_b32 v[4:5], v2 offset1:65
	v_add_u32_e32 v3, 0x800, v2
	ds_read2_b32 v[12:13], v3 offset0:8 offset1:73
	ds_read2_b32 v[0:1], v2 offset0:130 offset1:195
	ds_read2_b32 v[14:15], v3 offset0:138 offset1:203
	v_add_u32_e32 v3, 0x400, v2
	ds_read2_b32 v[6:7], v3 offset0:4 offset1:69
	v_add_u32_e32 v18, 0xc00, v2
	s_waitcnt lgkmcnt(2)
	v_cvt_pk_bf16_f32 v1, v0, v1
	v_cvt_pk_bf16_f32 v0, v4, v5
	v_cvt_pk_bf16_f32 v4, v12, v13
	v_add_u32_e32 v12, s14, v20
	ds_read2_b32 v[16:17], v18 offset0:12 offset1:77
	ds_read2_b32 v[2:3], v3 offset0:134 offset1:199
	ds_read2_b32 v[18:19], v18 offset0:142 offset1:207
	v_ashrrev_i32_e32 v13, 31, v12
	v_lshlrev_b64 v[12:13], 10, v[12:13]
	v_lshl_add_u64 v[12:13], s[20:21], 0, v[12:13]
	v_lshl_add_u64 v[12:13], v[12:13], 0, s[26:27]
	s_waitcnt lgkmcnt(1)
	v_cvt_pk_bf16_f32 v3, v2, v3
	v_cvt_pk_bf16_f32 v2, v6, v7
	v_lshl_add_u64 v[12:13], v[12:13], 0, v[148:149]
	s_waitcnt lgkmcnt(0)
	v_cvt_pk_bf16_f32 v7, v18, v19
	v_cvt_pk_bf16_f32 v6, v16, v17
	v_cvt_pk_bf16_f32 v5, v14, v15
	global_store_dwordx4 v[12:13], v[0:3], off sc1
	global_store_dwordx4 v[12:13], v[4:7], off offset:16 sc1

.LBB0_83:
	s_andn2_b64 vcc, exec, s[14:15]
	s_cbranch_vccnz .LBB0_52
	s_mul_hi_i32 s2, s84, 0x4d4873ed
	s_lshr_b32 s20, s2, 31
	s_ashr_i32 s2, s2, 5
	s_load_dwordx2 s[14:15], s[4:5], 0x48
	s_add_i32 s2, s2, s20
	s_mul_i32 s21, s2, 0xffffe580
	s_add_i32 s86, s45, s21
	s_ashr_i32 s87, s86, 31
	s_lshl_b32 s20, s2, 6
	v_mov_b32_e32 v12, v254
	s_lshl_b64 s[86:87], s[86:87], 2
	s_waitcnt lgkmcnt(0)
	s_add_u32 s14, s14, s86
	v_lshlrev_b32_e32 v13, 4, v12
	s_addc_u32 s15, s15, s87
	v_and_b32_e32 v148, 0xf0, v13
	v_ashrrev_i32_e32 v2, 4, v12
	v_lshl_add_u64 v[0:1], s[14:15], 0, v[148:149]
	s_mov_b64 s[14:15], 0x1a80000
	v_lshl_add_u64 v[4:5], v[0:1], 0, s[14:15]
	v_add_u32_e32 v14, s20, v2
	s_movk_i32 s21, 0x6a00
	v_mad_i64_i32 v[0:1], s[14:15], v14, s21, v[4:5]
	s_barrier
	v_mad_u64_u32 v[6:7], s[14:15], v2, s93, v[148:149]
	global_load_dwordx4 v[0:3], v[0:1], off
	v_add_u32_e32 v7, 0x1040, v6
	v_and_b32_e32 v21, 48, v13
	v_ashrrev_i32_e32 v20, 2, v12
	s_mulk_i32 s2, 0x1a80
	v_lshlrev_b32_e32 v148, 1, v21
	s_waitcnt vmcnt(0)
	ds_write2_b32 v6, v0, v1 offset1:1
	ds_write2_b32 v6, v2, v3 offset0:2 offset1:3
	v_add_u32_e32 v0, 16, v14
	v_mad_i64_i32 v[0:1], s[14:15], v0, s21, v[4:5]
	global_load_dwordx4 v[0:3], v[0:1], off
	s_waitcnt vmcnt(0)
	ds_write2_b32 v7, v0, v1 offset1:1
	v_add_u32_e32 v0, 0x1048, v6
	ds_write2_b32 v0, v2, v3 offset1:1
	v_add_u32_e32 v0, 32, v14
	v_mad_i64_i32 v[0:1], s[14:15], v0, s21, v[4:5]
	global_load_dwordx4 v[0:3], v[0:1], off
	v_add_u32_e32 v7, 0x2080, v6
	s_waitcnt vmcnt(0)
	ds_write2_b32 v7, v0, v1 offset1:1
	v_add_u32_e32 v0, 0x2088, v6
	ds_write2_b32 v0, v2, v3 offset1:1
	v_add_u32_e32 v0, 48, v14
	v_mad_i64_i32 v[0:1], s[14:15], v0, s21, v[4:5]
	global_load_dwordx4 v[0:3], v[0:1], off
	v_add_u32_e32 v4, 0x30c0, v6
	s_ashr_i32 s21, s20, 31
	s_waitcnt vmcnt(0)
	ds_write2_b32 v4, v0, v1 offset1:1
	v_add_u32_e32 v0, 0x30c8, v6
	ds_write2_b32 v0, v2, v3 offset1:1
	v_and_b32_e32 v0, -4, v12
	v_mul_u32_u24_e32 v1, 0x41, v21
	v_lshl_add_u32 v2, v1, 2, v0
	s_waitcnt lgkmcnt(0)
	s_barrier
	ds_read2_b32 v[4:5], v2 offset1:65
	v_add_u32_e32 v3, 0x800, v2
	ds_read2_b32 v[12:13], v3 offset0:8 offset1:73
	ds_read2_b32 v[0:1], v2 offset0:130 offset1:195
	ds_read2_b32 v[14:15], v3 offset0:138 offset1:203
	v_add_u32_e32 v3, 0x400, v2
	ds_read2_b32 v[6:7], v3 offset0:4 offset1:69
	v_add_u32_e32 v18, 0xc00, v2
	s_waitcnt lgkmcnt(2)
	v_cvt_pk_bf16_f32 v1, v0, v1
	v_cvt_pk_bf16_f32 v0, v4, v5
	v_cvt_pk_bf16_f32 v4, v12, v13
	v_subrev_u32_e32 v12, s2, v20
	v_add_u32_e32 v12, s45, v12
	ds_read2_b32 v[16:17], v18 offset0:12 offset1:77
	ds_read2_b32 v[2:3], v3 offset0:134 offset1:199
	ds_read2_b32 v[18:19], v18 offset0:142 offset1:207
	v_ashrrev_i32_e32 v13, 31, v12
	v_lshlrev_b64 v[12:13], 11, v[12:13]
	v_lshl_add_u64 v[12:13], s[30:31], 0, v[12:13]
	v_lshl_add_u64 v[12:13], s[20:21], 1, v[12:13]
	s_waitcnt lgkmcnt(1)
	v_cvt_pk_bf16_f32 v3, v2, v3
	v_cvt_pk_bf16_f32 v2, v6, v7
	v_lshl_add_u64 v[12:13], v[12:13], 0, v[148:149]
	s_waitcnt lgkmcnt(0)
	v_cvt_pk_bf16_f32 v7, v18, v19
	v_cvt_pk_bf16_f32 v6, v16, v17
	v_cvt_pk_bf16_f32 v5, v14, v15
	global_store_dwordx4 v[12:13], v[0:3], off sc1
	global_store_dwordx4 v[12:13], v[4:7], off offset:16 sc1
	s_branch .LBB0_52

.LBB0_206:
	v_add_f32_e32 v41, v29, v28
	v_add_f32_e32 v41, v30, v41
	v_add_f32_e32 v43, v25, v24
	v_add_f32_e32 v41, v31, v41
	v_add_f32_e32 v43, v26, v43
	v_add_f32_e32 v41, 0, v41
	v_add_f32_e32 v43, v27, v43
	v_add_f32_e32 v41, v43, v41
	v_add_f32_e32 v43, v21, v20
	v_add_f32_e32 v43, v22, v43
	v_add_f32_e32 v43, v23, v43
	v_add_f32_e32 v41, v43, v41
	v_add_f32_e32 v43, v17, v16
	v_add_f32_e32 v43, v18, v43
	v_add_f32_e32 v43, v19, v43
	v_add_f32_e32 v41, v43, v41
	s_nop 1
	v_add_f32_dpp v41, v41, v41 quad_perm:[1,0,3,2] row_mask:0xf bank_mask:0xf bound_ctrl:1
	s_nop 1
	v_add_f32_dpp v41, v41, v41 quad_perm:[2,3,0,1] row_mask:0xf bank_mask:0xf bound_ctrl:1
	s_nop 1
	v_add_f32_dpp v41, v41, v41 row_half_mirror row_mask:0xf bank_mask:0xf bound_ctrl:1
	s_nop 1
	v_add_f32_dpp v41, v41, v41 row_mirror row_mask:0xf bank_mask:0xf bound_ctrl:1
	ds_bpermute_b32 v43, v33, v41
	s_waitcnt lgkmcnt(0)
	v_add_f32_e32 v41, v41, v43
	ds_bpermute_b32 v43, v60, v41
	s_waitcnt lgkmcnt(0)
	v_add_f32_e32 v41, v41, v43
	v_mul_f32_e32 v56, 0x3a800000, v41
	v_pk_add_f32 v[54:55], v[28:29], v[56:57] op_sel_hi:[1,0] neg_lo:[0,1] neg_hi:[0,1]
	v_pk_add_f32 v[50:51], v[24:25], v[56:57] op_sel_hi:[1,0] neg_lo:[0,1] neg_hi:[0,1]
	v_pk_add_f32 v[52:53], v[26:27], v[56:57] op_sel_hi:[1,0] neg_lo:[0,1] neg_hi:[0,1]
	v_mov_b32_e32 v26, v55
	v_mov_b32_e32 v27, v51
	v_pk_add_f32 v[28:29], v[20:21], v[56:57] op_sel_hi:[1,0] neg_lo:[0,1] neg_hi:[0,1]
	v_pk_add_f32 v[16:17], v[16:17], v[56:57] op_sel_hi:[1,0] neg_lo:[0,1] neg_hi:[0,1]
	v_pk_add_f32 v[58:59], v[30:31], v[56:57] op_sel_hi:[1,0] neg_lo:[0,1] neg_hi:[0,1]
	v_mov_b32_e32 v24, v54
	v_mov_b32_e32 v25, v50
	v_pk_mul_f32 v[26:27], v[26:27], v[26:27]
	v_pk_add_f32 v[30:31], v[22:23], v[56:57] op_sel_hi:[1,0] neg_lo:[0,1] neg_hi:[0,1]
	v_mov_b32_e32 v22, v17
	v_mov_b32_e32 v23, v29
	v_pk_fma_f32 v[24:25], v[24:25], v[24:25], v[26:27]
	v_mov_b32_e32 v26, v58
	v_mov_b32_e32 v27, v52
	v_pk_add_f32 v[18:19], v[18:19], v[56:57] op_sel_hi:[1,0] neg_lo:[0,1] neg_hi:[0,1]
	v_mov_b32_e32 v20, v16
	v_mov_b32_e32 v21, v28
	v_pk_mul_f32 v[22:23], v[22:23], v[22:23]
	v_pk_fma_f32 v[24:25], v[26:27], v[26:27], v[24:25]
	v_mov_b32_e32 v26, v59
	v_mov_b32_e32 v27, v53
	v_pk_fma_f32 v[20:21], v[20:21], v[20:21], v[22:23]
	v_mov_b32_e32 v22, v18
	v_mov_b32_e32 v23, v30
	v_pk_fma_f32 v[24:25], v[26:27], v[26:27], v[24:25]
	v_pk_fma_f32 v[20:21], v[22:23], v[22:23], v[20:21]
	v_mov_b32_e32 v22, v19
	v_mov_b32_e32 v23, v31
	v_pk_fma_f32 v[20:21], v[22:23], v[22:23], v[20:21]
	v_add_f32_e32 v22, v24, v25
	v_add_f32_e32 v21, v21, v22
	v_add_f32_e32 v20, v20, v21
	s_nop 1
	v_add_f32_dpp v20, v20, v20 quad_perm:[1,0,3,2] row_mask:0xf bank_mask:0xf bound_ctrl:1
	s_nop 1
	v_add_f32_dpp v20, v20, v20 quad_perm:[2,3,0,1] row_mask:0xf bank_mask:0xf bound_ctrl:1
	s_nop 1
	v_add_f32_dpp v20, v20, v20 row_half_mirror row_mask:0xf bank_mask:0xf bound_ctrl:1
	s_nop 1
	v_add_f32_dpp v20, v20, v20 row_mirror row_mask:0xf bank_mask:0xf bound_ctrl:1
	ds_bpermute_b32 v21, v33, v20
	s_waitcnt lgkmcnt(0)
	v_add_f32_e32 v20, v20, v21
	ds_bpermute_b32 v21, v60, v20
	s_waitcnt lgkmcnt(0)
	v_add_f32_e32 v20, v20, v21
	v_mov_b32_e32 v21, 0x3727c5ac
	v_fmamk_f32 v20, v20, 0x3a800000, v21
	v_mul_f32_e32 v21, 0x4b800000, v20
	v_cmp_gt_f32_e32 vcc, s57, v20
	s_nop 1
	v_cndmask_b32_e32 v20, v20, v21, vcc
	v_rsq_f32_e32 v20, v20
	s_nop 0
	v_mul_f32_e32 v21, 0x45800000, v20
	v_cndmask_b32_e32 v57, v20, v21, vcc
	s_and_saveexec_b64 s[14:15], s[4:5]
	s_cbranch_execz .LBB0_208
	v_lshl_add_u64 v[20:21], v[46:47], 3, s[10:11]
	global_store_dwordx2 v[20:21], v[56:57], off sc1
.LBB0_208:
	s_or_b64 exec, exec, s[14:15]
	s_andn2_b64 vcc, exec, s[12:13]
	s_cbranch_vccnz .LBB0_203
	v_add_u32_e32 v20, 0xffffe000, v46
	v_lshrrev_b32_e32 v20, 11, v20
	v_add_u32_e32 v20, 1, v20
	v_cmp_lt_i32_e32 vcc, s34, v46
	v_mov_b32_e32 v26, v57
	v_lshlrev_b32_e32 v148, 2, v32
	v_cndmask_b32_e32 v22, 0, v20, vcc
	v_mov_b64_e32 v[20:21], s[8:9]
	v_mad_u64_u32 v[20:21], s[14:15], v22, s35, v[20:21]
	s_mov_b64 s[14:15], 0x3000
	s_nop 0
	v_lshl_add_u64 v[22:23], v[20:21], 0, s[14:15]
	s_mov_b64 s[14:15], 0x4000
	v_lshl_add_u64 v[24:25], v[20:21], 0, s[14:15]
	v_pk_mul_f32 v[20:21], v[58:59], v[26:27] op_sel_hi:[1,0]
	v_pk_mul_f32 v[58:59], v[54:55], v[26:27] op_sel_hi:[1,0]
	v_lshl_add_u64 v[66:67], v[24:25], 0, v[148:149]
	v_lshl_add_u64 v[70:71], v[22:23], 0, v[148:149]
	global_load_dwordx4 v[54:57], v[36:37], off
	global_load_dwordx4 v[62:65], v[34:35], off
	s_nop 0
	global_load_dwordx4 v[66:69], v[66:67], off
	s_nop 0
	global_load_dwordx4 v[70:73], v[70:71], off
	s_load_dwordx2 s[14:15], s[6:7], 0x120
	v_lshlrev_b32_e32 v148, 1, v32
	v_mov_b32_e32 v41, v149
	v_mov_b32_e32 v43, v149
	v_mov_b32_e32 v45, v149
	s_waitcnt vmcnt(2)
	v_pk_fma_f32 v[54:55], v[58:59], v[62:63], v[54:55]
	s_waitcnt vmcnt(1)
	v_pk_add_f32 v[58:59], v[66:67], 1.0 op_sel_hi:[1,0]
	v_pk_fma_f32 v[20:21], v[20:21], v[64:65], v[56:57]
	v_pk_add_f32 v[56:57], v[68:69], 1.0 op_sel_hi:[1,0]
	s_waitcnt vmcnt(0)
	v_pk_fma_f32 v[54:55], v[54:55], v[58:59], v[70:71]
	v_pk_fma_f32 v[20:21], v[20:21], v[56:57], v[72:73]
	v_cvt_pk_bf16_f32 v54, v54, v55
	v_cvt_pk_bf16_f32 v55, v20, v21
	s_waitcnt lgkmcnt(0)
	v_lshl_add_u64 v[20:21], v[48:49], 1, s[14:15]
	v_lshl_add_u64 v[48:49], v[20:21], 0, v[148:149]
	s_mov_b64 s[14:15], 0xe0c1000
	v_lshl_add_u64 v[20:21], v[48:49], 0, s[14:15]
	s_mov_b32 s14, 0xe0c1000
	v_add_co_u32_e32 v48, vcc, s14, v48
	v_pk_mul_f32 v[66:67], v[52:53], v[26:27] op_sel_hi:[1,0]
	s_nop 0
	v_addc_co_u32_e32 v49, vcc, 0, v49, vcc
	global_store_dwordx2 v[48:49], v[54:55], off sc1
	v_pk_mul_f32 v[56:57], v[50:51], v[26:27] op_sel_hi:[1,0]
	global_load_dwordx4 v[48:51], v[36:37], off offset:1024
	global_load_dwordx4 v[52:55], v[34:35], off offset:1024
	v_lshl_add_u64 v[58:59], v[24:25], 0, v[40:41]
	v_lshl_add_u64 v[62:63], v[22:23], 0, v[40:41]
	s_waitcnt vmcnt(0)
	v_pk_fma_f32 v[48:49], v[56:57], v[52:53], v[48:49]
	global_load_dwordx4 v[56:59], v[58:59], off
	s_nop 0
	global_load_dwordx4 v[62:65], v[62:63], off
	v_pk_fma_f32 v[50:51], v[66:67], v[54:55], v[50:51]
	v_lshl_add_u64 v[54:55], v[24:25], 0, v[42:43]
	s_waitcnt vmcnt(1)
	v_pk_add_f32 v[52:53], v[56:57], 1.0 op_sel_hi:[1,0]
	s_waitcnt vmcnt(0)
	v_pk_fma_f32 v[48:49], v[48:49], v[52:53], v[62:63]
	v_pk_add_f32 v[52:53], v[58:59], 1.0 op_sel_hi:[1,0]
	v_cvt_pk_bf16_f32 v48, v48, v49
	v_pk_fma_f32 v[50:51], v[50:51], v[52:53], v[64:65]
	v_pk_mul_f32 v[62:63], v[30:31], v[26:27] op_sel_hi:[1,0]
	v_cvt_pk_bf16_f32 v49, v50, v51
	global_store_dwordx2 v[20:21], v[48:49], off offset:512 sc1
	v_pk_mul_f32 v[52:53], v[28:29], v[26:27] op_sel_hi:[1,0]
	global_load_dwordx4 v[28:31], v[36:37], off offset:2048
	global_load_dwordx4 v[48:51], v[34:35], off offset:2048
	v_lshl_add_u64 v[56:57], v[22:23], 0, v[42:43]
	s_waitcnt vmcnt(0)
	v_pk_fma_f32 v[28:29], v[52:53], v[48:49], v[28:29]
	global_load_dwordx4 v[52:55], v[54:55], off
	s_nop 0
	global_load_dwordx4 v[56:59], v[56:57], off
	v_pk_fma_f32 v[30:31], v[62:63], v[50:51], v[30:31]
	s_waitcnt vmcnt(1)
	v_pk_add_f32 v[48:49], v[52:53], 1.0 op_sel_hi:[1,0]
	s_waitcnt vmcnt(0)
	v_pk_fma_f32 v[28:29], v[28:29], v[48:49], v[56:57]
	v_pk_add_f32 v[48:49], v[54:55], 1.0 op_sel_hi:[1,0]
	v_cvt_pk_bf16_f32 v28, v28, v29
	v_pk_fma_f32 v[30:31], v[30:31], v[48:49], v[58:59]
	v_lshl_add_u64 v[48:49], v[22:23], 0, v[44:45]
	v_cvt_pk_bf16_f32 v29, v30, v31
	global_store_dwordx2 v[20:21], v[28:29], off offset:1024 sc1
	v_pk_mul_f32 v[30:31], v[18:19], v[26:27] op_sel_hi:[1,0]
	v_pk_mul_f32 v[26:27], v[16:17], v[26:27] op_sel_hi:[1,0]
	v_lshl_add_u64 v[28:29], v[24:25], 0, v[44:45]
	global_load_dwordx4 v[16:19], v[36:37], off offset:3072
	global_load_dwordx4 v[22:25], v[34:35], off offset:3072
	s_waitcnt vmcnt(0)
	v_pk_fma_f32 v[16:17], v[26:27], v[22:23], v[16:17]
	global_load_dwordx4 v[26:29], v[28:29], off
	s_nop 0
	global_load_dwordx4 v[48:51], v[48:49], off
	v_pk_fma_f32 v[18:19], v[30:31], v[24:25], v[18:19]
	s_waitcnt vmcnt(1)
	v_pk_add_f32 v[22:23], v[26:27], 1.0 op_sel_hi:[1,0]
	s_waitcnt vmcnt(0)
	v_pk_fma_f32 v[16:17], v[16:17], v[22:23], v[48:49]
	v_pk_add_f32 v[22:23], v[28:29], 1.0 op_sel_hi:[1,0]
	v_cvt_pk_bf16_f32 v16, v16, v17
	v_pk_fma_f32 v[18:19], v[18:19], v[22:23], v[50:51]
	s_nop 0
	v_cvt_pk_bf16_f32 v17, v18, v19
	global_store_dwordx2 v[20:21], v[16:17], off offset:1536 sc1
	s_branch .LBB0_203

.LBB0_370:
	s_lshl_b64 s[16:17], s[96:97], 10
	s_add_u32 s2, s12, s16
	v_mov_b32_e32 v28, v254
	s_addc_u32 s16, s13, s17
	s_lshl_b64 s[20:21], s[6:7], 1
	s_barrier
	s_add_u32 s22, s2, s20
	v_lshrrev_b32_e32 v29, 2, v28
	v_and_b32_e32 v29, 0x1fffffec, v29
	s_movk_i32 s2, 0x88
	v_and_b32_e32 v28, 0x4f, v28
	v_mul_lo_u32 v29, v29, s2
	v_add_lshl_u32 v28, v29, v28, 1
	ds_read_u16 v29, v28 offset:36864
	ds_read_u16 v30, v28 offset:36896
	s_addc_u32 s23, s16, s21
	s_cmpk_lt_i32 s83, 0x80
	s_mov_b32 s2, 0
	s_waitcnt lgkmcnt(1)
	v_lshlrev_b32_e32 v29, 16, v29
	v_mul_f32_e32 v29, v32, v29
	v_cvt_pk_bf16_f32 v29, v29, s0
	ds_write_b16 v28, v29
	ds_read_u16 v29, v28 offset:37136
	s_waitcnt lgkmcnt(0)
	v_lshlrev_b32_e32 v29, 16, v29
	v_mul_f32_e32 v29, v33, v29
	v_cvt_pk_bf16_f32 v29, v29, s0
	ds_write_b16 v28, v29 offset:272
	ds_read_u16 v29, v28 offset:37408
	s_waitcnt lgkmcnt(0)
	v_lshlrev_b32_e32 v29, 16, v29
	v_mul_f32_e32 v29, v34, v29
	v_cvt_pk_bf16_f32 v29, v29, s0
	ds_write_b16 v28, v29 offset:544
	ds_read_u16 v29, v28 offset:37680
	s_waitcnt lgkmcnt(0)
	v_lshlrev_b32_e32 v29, 16, v29
	v_mul_f32_e32 v29, v35, v29
	v_cvt_pk_bf16_f32 v29, v29, s0
	ds_write_b16 v28, v29 offset:816
	v_lshlrev_b32_e32 v29, 16, v30
	v_mul_f32_e32 v24, v24, v29
	v_cvt_pk_bf16_f32 v24, v24, s0
	ds_write_b16 v28, v24 offset:32
	ds_read_u16 v24, v28 offset:37168
	s_waitcnt lgkmcnt(0)
	v_lshlrev_b32_e32 v24, 16, v24
	v_mul_f32_e32 v24, v25, v24
	v_cvt_pk_bf16_f32 v24, v24, s0
	ds_write_b16 v28, v24 offset:304
	ds_read_u16 v24, v28 offset:37440
	s_waitcnt lgkmcnt(0)
	v_lshlrev_b32_e32 v24, 16, v24
	v_mul_f32_e32 v24, v26, v24
	v_cvt_pk_bf16_f32 v24, v24, s0
	ds_write_b16 v28, v24 offset:576
	ds_read_u16 v24, v28 offset:37712
	s_waitcnt lgkmcnt(0)
	v_lshlrev_b32_e32 v24, 16, v24
	v_mul_f32_e32 v24, v27, v24
	v_cvt_pk_bf16_f32 v24, v24, s0
	ds_write_b16 v28, v24 offset:848
	ds_read_u16 v24, v28 offset:36928
	ds_read_u16 v25, v28 offset:36960
	s_waitcnt lgkmcnt(1)
	v_lshlrev_b32_e32 v24, 16, v24
	v_mul_f32_e32 v20, v20, v24
	v_cvt_pk_bf16_f32 v20, v20, s0
	ds_write_b16 v28, v20 offset:64
	ds_read_u16 v20, v28 offset:37200
	s_waitcnt lgkmcnt(0)
	v_lshlrev_b32_e32 v20, 16, v20
	v_mul_f32_e32 v20, v21, v20
	v_cvt_pk_bf16_f32 v20, v20, s0
	ds_write_b16 v28, v20 offset:336
	ds_read_u16 v20, v28 offset:37472
	s_waitcnt lgkmcnt(0)
	v_lshlrev_b32_e32 v20, 16, v20
	v_mul_f32_e32 v20, v22, v20
	v_cvt_pk_bf16_f32 v20, v20, s0
	ds_write_b16 v28, v20 offset:608
	ds_read_u16 v20, v28 offset:37744
	s_waitcnt lgkmcnt(0)
	v_lshlrev_b32_e32 v20, 16, v20
	v_mul_f32_e32 v20, v23, v20
	v_cvt_pk_bf16_f32 v20, v20, s0
	ds_write_b16 v28, v20 offset:880
	v_lshlrev_b32_e32 v20, 16, v25
	v_mul_f32_e32 v16, v16, v20
	v_cvt_pk_bf16_f32 v16, v16, s0
	ds_write_b16 v28, v16 offset:96
	ds_read_u16 v16, v28 offset:37232
	s_waitcnt lgkmcnt(0)
	v_lshlrev_b32_e32 v16, 16, v16
	v_mul_f32_e32 v16, v17, v16
	v_cvt_pk_bf16_f32 v16, v16, s0
	ds_write_b16 v28, v16 offset:368
	ds_read_u16 v16, v28 offset:37504
	s_waitcnt lgkmcnt(0)
	v_lshlrev_b32_e32 v16, 16, v16
	v_mul_f32_e32 v16, v18, v16
	v_cvt_pk_bf16_f32 v16, v16, s0
	ds_write_b16 v28, v16 offset:640
	ds_read_u16 v16, v28 offset:37776
	s_waitcnt lgkmcnt(0)
	v_lshlrev_b32_e32 v16, 16, v16
	v_mul_f32_e32 v16, v19, v16
	v_cvt_pk_bf16_f32 v16, v16, s0
	ds_write_b16 v28, v16 offset:912
	ds_read_u16 v16, v28 offset:41216
	s_waitcnt lgkmcnt(0)
	v_lshlrev_b32_e32 v16, 16, v16
	v_mul_f32_e32 v12, v12, v16
	v_cvt_pk_bf16_f32 v12, v12, s0
	ds_write_b16 v28, v12 offset:4352
	ds_read_u16 v12, v28 offset:41488
	s_waitcnt lgkmcnt(0)
	v_lshlrev_b32_e32 v12, 16, v12
	v_mul_f32_e32 v12, v13, v12
	v_cvt_pk_bf16_f32 v12, v12, s0
	ds_write_b16 v28, v12 offset:4624
	ds_read_u16 v12, v28 offset:41760
	s_waitcnt lgkmcnt(0)
	v_lshlrev_b32_e32 v12, 16, v12
	v_mul_f32_e32 v12, v14, v12
	v_cvt_pk_bf16_f32 v12, v12, s0
	ds_write_b16 v28, v12 offset:4896
	ds_read_u16 v12, v28 offset:42032
	s_waitcnt lgkmcnt(0)
	v_lshlrev_b32_e32 v12, 16, v12
	v_mul_f32_e32 v12, v15, v12
	v_cvt_pk_bf16_f32 v12, v12, s0
	ds_write_b16 v28, v12 offset:5168
	ds_read_u16 v12, v28 offset:41248
	s_waitcnt lgkmcnt(0)
	v_lshlrev_b32_e32 v12, 16, v12
	v_mul_f32_e32 v8, v8, v12
	v_cvt_pk_bf16_f32 v8, v8, s0
	ds_write_b16 v28, v8 offset:4384
	ds_read_u16 v8, v28 offset:41520
	s_waitcnt lgkmcnt(0)
	v_lshlrev_b32_e32 v8, 16, v8
	v_mul_f32_e32 v8, v9, v8
	v_cvt_pk_bf16_f32 v8, v8, s0
	ds_write_b16 v28, v8 offset:4656
	ds_read_u16 v8, v28 offset:41792
	s_waitcnt lgkmcnt(0)
	v_lshlrev_b32_e32 v8, 16, v8
	v_mul_f32_e32 v8, v10, v8
	v_cvt_pk_bf16_f32 v8, v8, s0
	ds_write_b16 v28, v8 offset:4928
	ds_read_u16 v8, v28 offset:42064
	s_waitcnt lgkmcnt(0)
	v_lshlrev_b32_e32 v8, 16, v8
	v_mul_f32_e32 v8, v11, v8
	v_cvt_pk_bf16_f32 v8, v8, s0
	ds_write_b16 v28, v8 offset:5200
	ds_read_u16 v8, v28 offset:41280
	s_waitcnt lgkmcnt(0)
	v_lshlrev_b32_e32 v8, 16, v8
	v_mul_f32_e32 v4, v4, v8
	v_cvt_pk_bf16_f32 v4, v4, s0
	ds_write_b16 v28, v4 offset:4416
	ds_read_u16 v4, v28 offset:41552
	v_mov_b32_e32 v8, v254
	s_waitcnt lgkmcnt(0)
	v_lshlrev_b32_e32 v4, 16, v4
	v_mul_f32_e32 v4, v5, v4
	v_cvt_pk_bf16_f32 v4, v4, s0
	ds_write_b16 v28, v4 offset:4688
	ds_read_u16 v4, v28 offset:41824
	s_waitcnt lgkmcnt(0)
	v_lshlrev_b32_e32 v4, 16, v4
	v_mul_f32_e32 v4, v6, v4
	v_cvt_pk_bf16_f32 v4, v4, s0
	ds_write_b16 v28, v4 offset:4960
	ds_read_u16 v4, v28 offset:42096
	s_waitcnt lgkmcnt(0)
	v_lshlrev_b32_e32 v4, 16, v4
	v_mul_f32_e32 v4, v7, v4
	v_cvt_pk_bf16_f32 v4, v4, s0
	ds_write_b16 v28, v4 offset:5232
	ds_read_u16 v4, v28 offset:41312
	s_waitcnt lgkmcnt(0)
	v_lshlrev_b32_e32 v4, 16, v4
	v_mul_f32_e32 v0, v0, v4
	v_cvt_pk_bf16_f32 v0, v0, s0
	ds_write_b16 v28, v0 offset:4448
	ds_read_u16 v0, v28 offset:41584
	s_waitcnt lgkmcnt(0)
	v_lshlrev_b32_e32 v0, 16, v0
	v_mul_f32_e32 v0, v1, v0
	v_cvt_pk_bf16_f32 v0, v0, s0
	ds_write_b16 v28, v0 offset:4720
	ds_read_u16 v0, v28 offset:41856
	s_waitcnt lgkmcnt(0)
	v_lshlrev_b32_e32 v0, 16, v0
	v_mul_f32_e32 v0, v2, v0
	v_cvt_pk_bf16_f32 v0, v0, s0
	ds_write_b16 v28, v0 offset:4992
	ds_read_u16 v0, v28 offset:42128
	s_waitcnt lgkmcnt(0)
	v_lshlrev_b32_e32 v0, 16, v0
	v_mul_f32_e32 v0, v3, v0
	v_cvt_pk_bf16_f32 v0, v0, s0
	ds_write_b16 v28, v0 offset:5264
	s_waitcnt lgkmcnt(0)
	s_barrier
	s_nop 0
	v_lshlrev_b32_e32 v0, 4, v8
	v_and_b32_e32 v148, 0xf0, v0
	v_ashrrev_i32_e32 v6, 4, v8
	v_mad_u64_u32 v[0:1], s[16:17], v6, s42, v[148:149]
	ds_read_b128 v[0:3], v0
	v_ashrrev_i32_e32 v7, 31, v6
	v_lshl_add_u64 v[4:5], s[22:23], 0, v[148:149]
	v_lshlrev_b64 v[6:7], 10, v[6:7]
	v_lshl_add_u64 v[6:7], v[4:5], 0, v[6:7]
	s_waitcnt lgkmcnt(0)
	global_store_dwordx4 v[6:7], v[0:3], off sc1
	s_nop 1
	v_add_u32_e32 v0, 0x100, v8
	v_ashrrev_i32_e32 v6, 4, v0
	v_mad_u64_u32 v[0:1], s[16:17], v6, s42, v[148:149]
	ds_read_b128 v[0:3], v0
	v_ashrrev_i32_e32 v7, 31, v6
	v_lshlrev_b64 v[6:7], 10, v[6:7]
	v_lshl_add_u64 v[6:7], v[4:5], 0, v[6:7]
	s_waitcnt lgkmcnt(0)
	global_store_dwordx4 v[6:7], v[0:3], off sc1
	s_nop 1
	v_add_u32_e32 v0, 0x200, v8
	v_ashrrev_i32_e32 v6, 4, v0
	v_mad_u64_u32 v[0:1], s[16:17], v6, s42, v[148:149]
	ds_read_b128 v[0:3], v0
	v_ashrrev_i32_e32 v7, 31, v6
	v_lshlrev_b64 v[6:7], 10, v[6:7]
	v_lshl_add_u64 v[6:7], v[4:5], 0, v[6:7]
	s_waitcnt lgkmcnt(0)
	global_store_dwordx4 v[6:7], v[0:3], off sc1
	s_nop 1
	v_add_u32_e32 v0, 0x300, v8
	v_ashrrev_i32_e32 v6, 4, v0
	v_mad_u64_u32 v[0:1], s[16:17], v6, s42, v[148:149]
	ds_read_b128 v[0:3], v0
	s_cselect_b64 s[16:17], -1, 0
	s_add_i32 s7, s96, 0xffffe000
	s_and_b64 s[22:23], s[16:17], exec
	v_ashrrev_i32_e32 v7, 31, v6
	s_cselect_b32 s25, s96, s7
	s_cselect_b32 s33, s97, 0
	s_cselect_b32 s46, 0, 8
	s_and_b64 s[22:23], s[90:91], exec
	v_lshlrev_b64 v[6:7], 10, v[6:7]
	s_cselect_b32 s22, s25, s96
	s_cselect_b32 s25, s46, 0x118
	v_lshl_add_u64 v[4:5], v[4:5], 0, v[6:7]
	s_cselect_b32 s23, s33, s97
	s_add_u32 s98, s8, s25
	s_waitcnt lgkmcnt(0)
	global_store_dwordx4 v[4:5], v[0:3], off sc1
	s_addc_u32 s99, s9, 0
	s_load_dwordx2 s[98:99], s[98:99], 0x0
	s_lshl_b64 s[22:23], s[22:23], 12
	v_add_u32_e32 v4, s6, v82
	v_ashrrev_i32_e32 v5, 31, v4
	v_lshlrev_b64 v[4:5], 2, v[4:5]
	s_waitcnt lgkmcnt(0)
	s_add_u32 s22, s98, s22
	s_addc_u32 s23, s99, s23
	s_lshr_b32 s7, s7, 11
	s_add_i32 s7, s7, 1
	s_and_b64 s[16:17], s[16:17], exec
	s_cselect_b32 s7, 0, s7
	s_mul_i32 s16, s82, 9
	s_add_i32 s7, s7, s16
	s_mul_hi_u32 s17, s7, 0x6000
	s_mulk_i32 s7, 0x6000
	s_add_u32 s16, s10, s7
	s_addc_u32 s17, s11, s17
	v_lshl_add_u64 v[8:9], s[16:17], 0, v[4:5]
	s_mov_b64 s[6:7], 0x1000
	v_lshl_add_u64 v[0:1], v[58:59], 0, s[20:21]
	v_lshl_add_u64 v[2:3], v[60:61], 0, s[20:21]
	v_lshl_add_u64 v[6:7], s[22:23], 0, v[4:5]
	v_lshl_add_u64 v[10:11], v[8:9], 0, s[6:7]
	s_branch .LBB0_372
.LBB0_371:
	v_lshlrev_b64 v[12:13], 10, v[14:15]
	v_lshl_add_u64 v[14:15], v[2:3], 0, v[12:13]
	v_lshl_add_u64 v[12:13], v[0:1], 0, v[12:13]
	v_lshl_add_u64 v[12:13], v[12:13], 0, s[78:79]
	s_addk_i32 s2, 0x400
	v_cvt_pk_bf16_f32 v18, v18, v19
	v_cvt_pk_bf16_f32 v19, v20, v21
	v_cvt_pk_bf16_f32 v20, v22, v23
	v_cvt_pk_bf16_f32 v21, v16, v17
	v_cndmask_b32_e64 v13, v13, v15, s[4:5]
	v_cndmask_b32_e64 v12, v12, v14, s[4:5]
	s_cmpk_eq_i32 s2, 0x800
	global_store_dwordx4 v[12:13], v[18:21], off sc1
	s_cbranch_scc1 .LBB0_359

.LBB0_376:
	v_lshlrev_b64 v[12:13], 10, v[14:15]
	v_lshl_add_u64 v[14:15], v[2:3], 0, v[12:13]
	v_lshl_add_u64 v[12:13], v[0:1], 0, v[12:13]
	v_lshl_add_u64 v[12:13], v[12:13], 0, s[78:79]
	v_cvt_pk_bf16_f32 v18, v18, v19
	v_cvt_pk_bf16_f32 v19, v20, v21
	v_cvt_pk_bf16_f32 v20, v22, v23
	v_cvt_pk_bf16_f32 v21, v16, v17
	v_cndmask_b32_e64 v13, v13, v15, s[4:5]
	v_cndmask_b32_e64 v12, v12, v14, s[4:5]
	global_store_dwordx4 v[12:13], v[18:21], off sc1
	v_add_u32_e32 v12, 0x100, v24
	v_ashrrev_i32_e32 v12, 5, v12
	v_cndmask_b32_e64 v14, 0, 1, s[92:93]
	v_ashrrev_i32_e32 v13, 31, v12
	v_cmp_ne_u32_e64 s[6:7], 1, v14
	s_andn2_b64 vcc, exec, s[92:93]
	s_mov_b64 s[16:17], -1
	s_cbranch_vccnz .LBB0_378
	v_lshl_add_u64 v[14:15], v[12:13], 0, s[96:97]
	v_lshl_add_u64 v[16:17], v[14:15], 3, s[94:95]
	global_load_dwordx2 v[54:55], v[16:17], off
	s_nop 0
	global_load_dwordx4 v[16:19], v[10:11], off offset:16
	global_load_dwordx4 v[20:23], v[10:11], off
	s_load_dwordx4 s[20:23], s[8:9], 0x108
	v_lshlrev_b64 v[26:27], 12, v[12:13]
	v_lshl_add_u64 v[30:31], v[6:7], 0, v[26:27]
	global_load_dwordx4 v[26:29], v[30:31], off
	s_nop 0
	global_load_dwordx4 v[30:33], v[30:31], off offset:16
	s_mov_b64 s[16:17], 0
	s_waitcnt vmcnt(13) lgkmcnt(0)
	v_lshl_add_u64 v[42:43], s[20:21], 0, v[4:5]
	s_waitcnt vmcnt(12)
	v_lshl_add_u64 v[46:47], s[22:23], 0, v[4:5]
	global_load_dwordx4 v[34:37], v[46:47], off
	global_load_dwordx4 v[38:41], v[42:43], off
	s_nop 0
	global_load_dwordx4 v[42:45], v[42:43], off offset:16
	s_nop 0
	global_load_dwordx4 v[46:49], v[46:47], off offset:16
	s_nop 0
	global_load_dwordx4 v[50:53], v[8:9], off
	global_load_dwordx4 v[62:65], v[8:9], off offset:16
	s_waitcnt vmcnt(9)
	v_pk_add_f32 v[66:67], v[18:19], 1.0 op_sel_hi:[1,0]
	s_waitcnt vmcnt(8)
	v_pk_add_f32 v[20:21], v[20:21], 1.0 op_sel_hi:[1,0]
	v_pk_add_f32 v[22:23], v[22:23], 1.0 op_sel_hi:[1,0]
	v_pk_add_f32 v[16:17], v[16:17], 1.0 op_sel_hi:[1,0]
	s_waitcnt vmcnt(7)
	v_pk_add_f32 v[18:19], v[26:27], v[54:55] op_sel_hi:[1,0] neg_lo:[0,1] neg_hi:[0,1]
	v_pk_add_f32 v[26:27], v[28:29], v[54:55] op_sel_hi:[1,0] neg_lo:[0,1] neg_hi:[0,1]
	s_waitcnt vmcnt(6)
	v_pk_add_f32 v[28:29], v[30:31], v[54:55] op_sel_hi:[1,0] neg_lo:[0,1] neg_hi:[0,1]
	v_pk_add_f32 v[30:31], v[32:33], v[54:55] op_sel_hi:[1,0] neg_lo:[0,1] neg_hi:[0,1]
	v_pk_mul_f32 v[18:19], v[54:55], v[18:19] op_sel:[1,0]
	v_pk_mul_f32 v[26:27], v[54:55], v[26:27] op_sel:[1,0]
	v_pk_mul_f32 v[28:29], v[54:55], v[28:29] op_sel:[1,0]
	v_pk_mul_f32 v[30:31], v[54:55], v[30:31] op_sel:[1,0]
	s_waitcnt vmcnt(4)
	v_pk_fma_f32 v[18:19], v[38:39], v[18:19], v[34:35]
	v_pk_fma_f32 v[26:27], v[40:41], v[26:27], v[36:37]
	s_waitcnt vmcnt(2)
	v_pk_fma_f32 v[28:29], v[42:43], v[28:29], v[46:47]
	v_pk_fma_f32 v[30:31], v[44:45], v[30:31], v[48:49]
	s_waitcnt vmcnt(1)
	v_pk_fma_f32 v[18:19], v[18:19], v[20:21], v[50:51]
	v_pk_fma_f32 v[20:21], v[26:27], v[22:23], v[52:53]
	s_waitcnt vmcnt(0)
	v_pk_fma_f32 v[22:23], v[28:29], v[16:17], v[62:63]
	v_pk_fma_f32 v[16:17], v[30:31], v[66:67], v[64:65]

.LBB0_380:
	v_lshlrev_b64 v[12:13], 10, v[14:15]
	v_lshl_add_u64 v[14:15], v[2:3], 0, v[12:13]
	v_lshl_add_u64 v[12:13], v[0:1], 0, v[12:13]
	v_lshl_add_u64 v[12:13], v[12:13], 0, s[78:79]
	v_cvt_pk_bf16_f32 v18, v18, v19
	v_cvt_pk_bf16_f32 v19, v20, v21
	v_cvt_pk_bf16_f32 v20, v22, v23
	v_cvt_pk_bf16_f32 v21, v16, v17
	v_cndmask_b32_e64 v13, v13, v15, s[4:5]
	v_cndmask_b32_e64 v12, v12, v14, s[4:5]
	global_store_dwordx4 v[12:13], v[18:21], off sc1
	v_add_u32_e32 v12, 0x200, v24
	v_ashrrev_i32_e32 v12, 5, v12
	v_ashrrev_i32_e32 v13, 31, v12
	s_and_b64 vcc, exec, s[6:7]
	s_mov_b64 s[16:17], -1
	s_cbranch_vccnz .LBB0_382
	v_lshl_add_u64 v[14:15], v[12:13], 0, s[96:97]
	v_lshl_add_u64 v[16:17], v[14:15], 3, s[94:95]
	global_load_dwordx2 v[54:55], v[16:17], off
	s_nop 0
	global_load_dwordx4 v[16:19], v[10:11], off offset:16
	global_load_dwordx4 v[20:23], v[10:11], off
	s_load_dwordx4 s[20:23], s[8:9], 0x108
	v_lshlrev_b64 v[26:27], 12, v[12:13]
	v_lshl_add_u64 v[30:31], v[6:7], 0, v[26:27]
	global_load_dwordx4 v[26:29], v[30:31], off
	s_nop 0
	global_load_dwordx4 v[30:33], v[30:31], off offset:16
	s_mov_b64 s[16:17], 0
	s_waitcnt vmcnt(14) lgkmcnt(0)
	v_lshl_add_u64 v[42:43], s[20:21], 0, v[4:5]
	s_waitcnt vmcnt(13)
	v_lshl_add_u64 v[46:47], s[22:23], 0, v[4:5]
	global_load_dwordx4 v[34:37], v[46:47], off
	global_load_dwordx4 v[38:41], v[42:43], off
	s_nop 0
	global_load_dwordx4 v[42:45], v[42:43], off offset:16
	s_nop 0
	global_load_dwordx4 v[46:49], v[46:47], off offset:16
	s_nop 0
	global_load_dwordx4 v[50:53], v[8:9], off
	global_load_dwordx4 v[62:65], v[8:9], off offset:16
	s_waitcnt vmcnt(9)
	v_pk_add_f32 v[66:67], v[18:19], 1.0 op_sel_hi:[1,0]
	s_waitcnt vmcnt(8)
	v_pk_add_f32 v[20:21], v[20:21], 1.0 op_sel_hi:[1,0]
	v_pk_add_f32 v[22:23], v[22:23], 1.0 op_sel_hi:[1,0]
	v_pk_add_f32 v[16:17], v[16:17], 1.0 op_sel_hi:[1,0]
	s_waitcnt vmcnt(7)
	v_pk_add_f32 v[18:19], v[26:27], v[54:55] op_sel_hi:[1,0] neg_lo:[0,1] neg_hi:[0,1]
	v_pk_add_f32 v[26:27], v[28:29], v[54:55] op_sel_hi:[1,0] neg_lo:[0,1] neg_hi:[0,1]
	s_waitcnt vmcnt(6)
	v_pk_add_f32 v[28:29], v[30:31], v[54:55] op_sel_hi:[1,0] neg_lo:[0,1] neg_hi:[0,1]
	v_pk_add_f32 v[30:31], v[32:33], v[54:55] op_sel_hi:[1,0] neg_lo:[0,1] neg_hi:[0,1]
	v_pk_mul_f32 v[18:19], v[54:55], v[18:19] op_sel:[1,0]
	v_pk_mul_f32 v[26:27], v[54:55], v[26:27] op_sel:[1,0]
	v_pk_mul_f32 v[28:29], v[54:55], v[28:29] op_sel:[1,0]
	v_pk_mul_f32 v[30:31], v[54:55], v[30:31] op_sel:[1,0]
	s_waitcnt vmcnt(4)
	v_pk_fma_f32 v[18:19], v[38:39], v[18:19], v[34:35]
	v_pk_fma_f32 v[26:27], v[40:41], v[26:27], v[36:37]
	s_waitcnt vmcnt(2)
	v_pk_fma_f32 v[28:29], v[42:43], v[28:29], v[46:47]
	v_pk_fma_f32 v[30:31], v[44:45], v[30:31], v[48:49]
	s_waitcnt vmcnt(1)
	v_pk_fma_f32 v[18:19], v[18:19], v[20:21], v[50:51]
	v_pk_fma_f32 v[20:21], v[26:27], v[22:23], v[52:53]
	s_waitcnt vmcnt(0)
	v_pk_fma_f32 v[22:23], v[28:29], v[16:17], v[62:63]
	v_pk_fma_f32 v[16:17], v[30:31], v[66:67], v[64:65]

.LBB0_384:
	v_lshlrev_b64 v[12:13], 10, v[14:15]
	v_lshl_add_u64 v[14:15], v[2:3], 0, v[12:13]
	v_lshl_add_u64 v[12:13], v[0:1], 0, v[12:13]
	v_lshl_add_u64 v[12:13], v[12:13], 0, s[78:79]
	v_cvt_pk_bf16_f32 v18, v18, v19
	v_cvt_pk_bf16_f32 v19, v20, v21
	v_cvt_pk_bf16_f32 v20, v22, v23
	v_cvt_pk_bf16_f32 v21, v16, v17
	v_cndmask_b32_e64 v13, v13, v15, s[4:5]
	v_cndmask_b32_e64 v12, v12, v14, s[4:5]
	global_store_dwordx4 v[12:13], v[18:21], off sc1
	v_add_u32_e32 v12, 0x300, v24
	v_ashrrev_i32_e32 v12, 5, v12
	v_ashrrev_i32_e32 v13, 31, v12
	s_and_b64 vcc, exec, s[6:7]
	s_mov_b64 s[6:7], -1
	s_cbranch_vccnz .LBB0_386
	v_lshl_add_u64 v[14:15], v[12:13], 0, s[96:97]
	v_lshl_add_u64 v[16:17], v[14:15], 3, s[94:95]
	global_load_dwordx2 v[62:63], v[16:17], off
	s_nop 0
	global_load_dwordx4 v[16:19], v[10:11], off offset:16
	global_load_dwordx4 v[20:23], v[10:11], off
	s_load_dwordx4 s[20:23], s[8:9], 0x108
	v_lshlrev_b64 v[24:25], 12, v[12:13]
	v_lshl_add_u64 v[28:29], v[6:7], 0, v[24:25]
	global_load_dwordx4 v[24:27], v[28:29], off
	s_nop 0
	global_load_dwordx4 v[28:31], v[28:29], off offset:16
	s_mov_b64 s[6:7], 0
	s_waitcnt vmcnt(15) lgkmcnt(0)
	v_lshl_add_u64 v[40:41], s[20:21], 0, v[4:5]
	s_waitcnt vmcnt(14)
	v_lshl_add_u64 v[44:45], s[22:23], 0, v[4:5]
	global_load_dwordx4 v[32:35], v[44:45], off
	global_load_dwordx4 v[36:39], v[40:41], off
	s_nop 0
	global_load_dwordx4 v[40:43], v[40:41], off offset:16
	s_nop 0
	global_load_dwordx4 v[44:47], v[44:45], off offset:16
	s_nop 0
	global_load_dwordx4 v[48:51], v[8:9], off
	global_load_dwordx4 v[52:55], v[8:9], off offset:16
	s_waitcnt vmcnt(9)
	v_pk_add_f32 v[64:65], v[18:19], 1.0 op_sel_hi:[1,0]
	s_waitcnt vmcnt(8)
	v_pk_add_f32 v[20:21], v[20:21], 1.0 op_sel_hi:[1,0]
	v_pk_add_f32 v[22:23], v[22:23], 1.0 op_sel_hi:[1,0]
	v_pk_add_f32 v[16:17], v[16:17], 1.0 op_sel_hi:[1,0]
	s_waitcnt vmcnt(7)
	v_pk_add_f32 v[18:19], v[24:25], v[62:63] op_sel_hi:[1,0] neg_lo:[0,1] neg_hi:[0,1]
	v_pk_add_f32 v[24:25], v[26:27], v[62:63] op_sel_hi:[1,0] neg_lo:[0,1] neg_hi:[0,1]
	s_waitcnt vmcnt(6)
	v_pk_add_f32 v[26:27], v[28:29], v[62:63] op_sel_hi:[1,0] neg_lo:[0,1] neg_hi:[0,1]
	v_pk_add_f32 v[28:29], v[30:31], v[62:63] op_sel_hi:[1,0] neg_lo:[0,1] neg_hi:[0,1]
	v_pk_mul_f32 v[18:19], v[62:63], v[18:19] op_sel:[1,0]
	v_pk_mul_f32 v[24:25], v[62:63], v[24:25] op_sel:[1,0]
	v_pk_mul_f32 v[26:27], v[62:63], v[26:27] op_sel:[1,0]
	v_pk_mul_f32 v[28:29], v[62:63], v[28:29] op_sel:[1,0]
	s_waitcnt vmcnt(4)
	v_pk_fma_f32 v[18:19], v[36:37], v[18:19], v[32:33]
	v_pk_fma_f32 v[24:25], v[38:39], v[24:25], v[34:35]
	s_waitcnt vmcnt(2)
	v_pk_fma_f32 v[26:27], v[40:41], v[26:27], v[44:45]
	v_pk_fma_f32 v[28:29], v[42:43], v[28:29], v[46:47]
	s_waitcnt vmcnt(1)
	v_pk_fma_f32 v[18:19], v[18:19], v[20:21], v[48:49]
	v_pk_fma_f32 v[20:21], v[24:25], v[22:23], v[50:51]
	s_waitcnt vmcnt(0)
	v_pk_fma_f32 v[22:23], v[26:27], v[16:17], v[52:53]
	v_pk_fma_f32 v[16:17], v[28:29], v[64:65], v[54:55]

.LBB0_577:
	v_add_u32_e32 v67, s11, v70
	v_ashrrev_i32_e32 v76, 4, v67
	v_mad_u64_u32 v[72:73], s[14:15], v76, s42, v[66:67]
	ds_read_b128 v[72:75], v72 offset:32768
	v_ashrrev_i32_e32 v77, 31, v76
	v_lshl_add_u64 v[76:77], s[22:23], 0, v[76:77]
	v_lshlrev_b64 v[76:77], 9, v[76:77]
	v_lshl_add_u64 v[80:81], v[68:69], 0, v[76:77]
	s_waitcnt lgkmcnt(0)
	v_and_b32_e32 v77, 0xffff0000, v72
	v_lshlrev_b32_e32 v76, 16, v72
	v_and_b32_e32 v79, 0xffff0000, v73
	v_lshlrev_b32_e32 v78, 16, v73
	global_store_dwordx4 v[80:81], v[76:79], off sc1
	v_add_u32_e32 v67, 0x100, v67
	s_addk_i32 s11, 0x200
	v_and_b32_e32 v77, 0xffff0000, v74
	v_lshlrev_b32_e32 v76, 16, v74
	v_and_b32_e32 v79, 0xffff0000, v75
	v_lshlrev_b32_e32 v78, 16, v75
	global_store_dwordx4 v[80:81], v[76:79], off offset:16 sc1
	s_cmpk_lg_i32 s11, 0x800
	s_nop 0
	v_ashrrev_i32_e32 v76, 4, v67
	v_mad_u64_u32 v[72:73], s[14:15], v76, s42, v[66:67]
	ds_read_b128 v[72:75], v72 offset:32768
	v_ashrrev_i32_e32 v77, 31, v76
	v_lshl_add_u64 v[76:77], s[22:23], 0, v[76:77]
	v_lshlrev_b64 v[76:77], 9, v[76:77]
	v_lshl_add_u64 v[80:81], v[68:69], 0, v[76:77]
	s_waitcnt lgkmcnt(0)
	v_and_b32_e32 v77, 0xffff0000, v72
	v_lshlrev_b32_e32 v76, 16, v72
	v_and_b32_e32 v79, 0xffff0000, v73
	v_lshlrev_b32_e32 v78, 16, v73
	global_store_dwordx4 v[80:81], v[76:79], off sc1
	s_nop 1
	v_and_b32_e32 v77, 0xffff0000, v74
	v_lshlrev_b32_e32 v76, 16, v74
	v_and_b32_e32 v79, 0xffff0000, v75
	v_lshlrev_b32_e32 v78, 16, v75
	global_store_dwordx4 v[80:81], v[76:79], off offset:16 sc1
	s_cbranch_scc1 .LBB0_577
	s_branch .LBB0_581

.LBB0_582:
	s_addk_i32 s17, 0x200
	s_waitcnt lgkmcnt(0)
	v_perm_b32 v77, v79, v78, s39
	v_perm_b32 v76, v75, v74, s39
	v_perm_b32 v75, v73, v72, s39
	v_perm_b32 v74, v71, v69, s39
	v_lshl_add_u64 v[66:67], v[64:65], 1, v[66:67]
	s_cmpk_eq_i32 s17, 0x800
	global_store_dwordx4 v[66:67], v[74:77], off sc1
	s_cbranch_scc1 .LBB0_591

.LBB0_587:
	s_waitcnt lgkmcnt(0)
	v_perm_b32 v77, v80, v77, s39
	v_perm_b32 v76, v76, v75, s39
	v_perm_b32 v75, v74, v73, s39
	v_perm_b32 v74, v72, v71, s39
	v_lshl_add_u64 v[66:67], v[64:65], 1, v[66:67]
	global_store_dwordx4 v[66:67], v[74:77], off sc1
	v_add_u32_e32 v66, 0x100, v69
	s_andn2_b64 vcc, exec, s[8:9]
	v_ashrrev_i32_e32 v76, 10, v66
	v_bfe_u32 v77, v66, 4, 6
	v_lshlrev_b32_e32 v66, 7, v76
	v_lshl_or_b32 v66, v77, 1, v66
	v_add_u32_e32 v66, v66, v68
	ds_read_u16 v69, v66 offset:32768
	ds_read_u16 v71, v66 offset:33040
	ds_read_u16 v72, v66 offset:33312
	ds_read_u16 v73, v66 offset:33584
	ds_read_u16 v74, v66 offset:33856
	ds_read_u16 v75, v66 offset:34128
	ds_read_u16 v78, v66 offset:34400
	ds_read_u16 v79, v66 offset:34672
	s_mov_b64 s[10:11], -1
	s_cbranch_vccnz .LBB0_589
	v_add_u32_e32 v66, s15, v76
	v_ashrrev_i32_e32 v67, 31, v66
	v_lshlrev_b64 v[66:67], 15, v[66:67]
	v_lshl_add_u64 v[66:67], s[84:85], 0, v[66:67]
	v_lshlrev_b32_e32 v148, 9, v77
	v_lshl_add_u64 v[66:67], v[66:67], 0, v[148:149]
	s_lshl_b32 s26, s13, 1
	v_lshl_add_u64 v[66:67], v[66:67], 0, s[26:27]
	s_mov_b64 s[10:11], 0

.LBB0_599:
	v_ashrrev_i32_e32 v23, 31, v22
	v_lshlrev_b64 v[32:33], 10, v[22:23]
	v_lshl_add_u64 v[32:33], s[94:95], 0, v[32:33]
	v_lshlrev_b32_e32 v148, 1, v16
	v_lshl_add_u64 v[32:33], v[32:33], 0, v[148:149]
	v_lshlrev_b32_e32 v148, 1, v12
	v_lshl_add_u64 v[32:33], v[32:33], 0, v[148:149]
	v_add_co_u32_e32 v32, vcc, 0x62c0000, v32
	s_nop 1
	v_addc_co_u32_e32 v33, vcc, 0, v33, vcc
	global_store_dwordx4 v[32:33], v[8:11], off offset:2048 sc1
	s_cbranch_execnz .LBB0_594
.LBB0_600:
	s_and_saveexec_b64 s[14:15], s[12:13]
	s_xor_b64 s[12:13], exec, s[14:15]
	s_cbranch_execz .LBB0_602
	v_ashrrev_i32_e32 v32, 8, v22
	v_lshl_or_b32 v34, v32, 1, v17
	v_ashrrev_i32_e32 v35, 31, v34
	v_lshlrev_b64 v[34:35], 15, v[34:35]
	v_mov_b32_e32 v23, 7
	v_lshl_add_u64 v[34:35], s[88:89], 0, v[34:35]
	v_lshlrev_b32_sdwa v148, v23, v22 dst_sel:DWORD dst_unused:UNUSED_PAD src0_sel:DWORD src1_sel:BYTE_0
	v_lshl_add_u64 v[34:35], v[34:35], 0, v[148:149]
	v_lshlrev_b32_e32 v148, 1, v12
	v_lshl_add_u64 v[34:35], v[34:35], 0, v[148:149]
	global_store_dwordx4 v[34:35], v[8:11], off sc1
	s_load_dwordx2 s[14:15], s[28:29], 0x118
	v_ashrrev_i32_e32 v33, 31, v32
	v_lshlrev_b64 v[8:9], 9, v[32:33]
	v_lshl_add_u64 v[8:9], v[8:9], 0, s[86:87]
	v_or_b32_sdwa v8, v8, v22 dst_sel:DWORD dst_unused:UNUSED_PAD src0_sel:DWORD src1_sel:BYTE_0
	v_lshlrev_b64 v[8:9], 9, v[8:9]
	s_waitcnt lgkmcnt(0)
	v_lshl_add_u64 v[8:9], s[14:15], 0, v[8:9]
	v_lshlrev_b32_e32 v148, 2, v16
	v_lshl_add_u64 v[8:9], v[8:9], 0, v[148:149]
	v_lshlrev_b32_e32 v148, 2, v12
	v_lshl_add_u64 v[8:9], v[8:9], 0, v[148:149]
	s_mov_b64 s[14:15], 0x6000000
	v_lshl_add_u64 v[10:11], v[8:9], 0, s[14:15]
	v_add_co_u32_e32 v8, vcc, 0x6000000, v8
	s_nop 1
	v_addc_co_u32_e32 v9, vcc, 0, v9, vcc
	global_store_dwordx4 v[8:9], v[4:7], off sc1
	global_store_dwordx4 v[10:11], v[0:3], off offset:16 sc1
.LBB0_602:
	s_andn2_saveexec_b64 s[12:13], s[12:13]
	s_cbranch_execz .LBB0_593
	v_add_u32_e32 v0, 0xffffe000, v22
	v_lshrrev_b32_e32 v0, 10, v0
	s_mov_b32 s14, 0x3ffffe
	v_and_or_b32 v0, v0, s14, v17
	v_add_u32_e32 v148, 0x200, v31
	s_movk_i32 s14, 0xa00
	v_mad_u64_u32 v[0:1], s[14:15], v0, s14, v[148:149]
	v_lshlrev_b64 v[0:1], 7, v[0:1]
	v_lshl_add_u64 v[0:1], v[20:21], 0, v[0:1]
	global_store_dwordx4 v[0:1], v[8:11], off sc1
	s_branch .LBB0_593

.LBB0_607:
	s_ashr_i32 s14, s12, 3
	v_mov_b32_e32 v1, v254
	s_and_b32 s17, s14, -2
	s_and_b32 s13, s2, 0x1c0
	v_ashrrev_i32_e32 v0, 2, v1
	s_add_i32 s14, s17, s82
	s_waitcnt vmcnt(0)
	s_barrier
	v_add_u32_e32 v34, s13, v0
	s_load_dwordx4 s[4:7], s[28:29], 0x10
	s_ashr_i32 s15, s14, 31
	v_ashrrev_i32_e32 v35, 31, v34
	s_lshl_b64 s[14:15], s[14:15], 10
	s_bfe_u32 s16, s12, 0x10003
	v_lshl_add_u64 v[2:3], v[34:35], 1, s[14:15]
	v_lshlrev_b32_e32 v1, 4, v1
	v_or_b32_e32 v2, s16, v2
	v_and_b32_e32 v1, 48, v1
	v_lshlrev_b64 v[2:3], 8, v[2:3]
	s_waitcnt lgkmcnt(0)
	v_lshl_add_u64 v[4:5], s[6:7], 0, v[2:3]
	v_lshlrev_b32_e32 v148, 2, v1
	v_lshl_add_u64 v[2:3], s[4:5], 0, v[2:3]
	v_lshl_add_u64 v[14:15], v[4:5], 0, v[148:149]
	v_lshl_add_u64 v[30:31], v[2:3], 0, v[148:149]
	global_load_dwordx4 v[2:5], v[14:15], off offset:48
	global_load_dwordx4 v[6:9], v[14:15], off offset:32
	global_load_dwordx4 v[10:13], v[14:15], off offset:16
	s_nop 0
	global_load_dwordx4 v[14:17], v[14:15], off
	s_nop 0
	global_load_dwordx4 v[18:21], v[30:31], off offset:48
	global_load_dwordx4 v[22:25], v[30:31], off offset:32
	global_load_dwordx4 v[26:29], v[30:31], off offset:16
	s_nop 0
	global_load_dwordx4 v[30:33], v[30:31], off
	v_lshlrev_b32_e32 v148, 1, v1
	s_or_b32 s4, s17, s16
	v_mov_b32_e32 v36, 0xa00
	v_mad_i64_i32 v[34:35], s[6:7], s4, v36, v[34:35]
	v_lshlrev_b64 v[34:35], 7, v[34:35]
	s_movk_i32 s6, 0x8e
	v_lshl_add_u64 v[34:35], s[8:9], 0, v[34:35]
	s_ashr_i32 s5, s4, 31
	v_lshl_add_u64 v[34:35], v[34:35], 0, v[148:149]
	s_lshl_b64 s[4:5], s[4:5], 6
	s_lshl_b32 s26, s13, 1
	s_add_i32 s12, s12, s18
	s_add_i32 s2, s2, s91
	s_cmpk_gt_i32 s12, 0x7f
	s_waitcnt vmcnt(7)
	v_cvt_pk_bf16_f32 v2, v2, s0
	s_waitcnt vmcnt(6)
	v_cvt_pk_bf16_f32 v6, v6, s0
	s_waitcnt vmcnt(5)
	v_cvt_pk_bf16_f32 v10, v10, s0
	s_waitcnt vmcnt(4)
	v_cvt_pk_bf16_f32 v14, v14, s0
	s_waitcnt vmcnt(2)
	v_cvt_pk_bf16_f32 v22, v22, v23
	v_cvt_pk_bf16_f32 v23, v24, v25
	v_cvt_pk_bf16_f32 v24, v18, v19
	v_lshlrev_b32_e32 v18, 1, v0
	v_mad_u32_u24 v1, v1, s98, v18
	ds_write_b16 v1, v14
	v_cvt_pk_bf16_f32 v14, v15, s0
	ds_write_b16 v1, v10 offset:576
	v_cvt_pk_bf16_f32 v10, v11, s0
	ds_write_b16 v1, v6 offset:1152
	v_cvt_pk_bf16_f32 v6, v7, s0
	ds_write_b16 v1, v2 offset:1728
	v_cvt_pk_bf16_f32 v2, v3, s0
	ds_write_b16 v1, v14 offset:144
	v_cvt_pk_bf16_f32 v14, v16, s0
	ds_write_b16 v1, v10 offset:720
	v_cvt_pk_bf16_f32 v10, v12, s0
	ds_write_b16 v1, v6 offset:1296
	v_cvt_pk_bf16_f32 v6, v8, s0
	ds_write_b16 v1, v2 offset:1872
	v_cvt_pk_bf16_f32 v2, v4, s0
	ds_write_b16 v1, v14 offset:288
	v_cvt_pk_bf16_f32 v14, v17, s0
	ds_write_b16 v1, v10 offset:864
	v_cvt_pk_bf16_f32 v10, v13, s0
	ds_write_b16 v1, v6 offset:1440
	v_cvt_pk_bf16_f32 v6, v9, s0
	ds_write_b16 v1, v2 offset:2016
	v_cvt_pk_bf16_f32 v2, v5, s0
	ds_write_b16 v1, v14 offset:432
	ds_write_b16 v1, v10 offset:1008
	ds_write_b16 v1, v6 offset:1584
	ds_write_b16 v1, v2 offset:2160
	v_mul_lo_u32 v1, v0, s6
	s_waitcnt vmcnt(0)
	v_cvt_pk_bf16_f32 v30, v30, v31
	v_cvt_pk_bf16_f32 v31, v32, v33
	v_cvt_pk_bf16_f32 v32, v26, v27
	v_cvt_pk_bf16_f32 v33, v28, v29
	v_cvt_pk_bf16_f32 v25, v20, v21
	v_add3_u32 v1, v18, v1, v148
	global_store_dwordx4 v[34:35], v[30:33], off sc1
	global_store_dwordx4 v[34:35], v[22:25], off offset:16 sc1
	s_waitcnt lgkmcnt(0)
	s_barrier
	ds_read_b128 v[2:5], v1
	ds_read_b128 v[6:9], v1 offset:16
	v_ashrrev_i32_e32 v1, 31, v0
	v_lshl_add_u64 v[0:1], s[4:5], 0, v[0:1]
	v_mov_b64_e32 v[10:11], s[10:11]
	v_mad_u64_u32 v[10:11], s[4:5], v0, s19, v[10:11]
	v_mad_i32_i24 v11, v1, s19, v11
	v_lshl_add_u64 v[0:1], v[10:11], 0, s[26:27]
	v_lshl_add_u64 v[0:1], v[0:1], 0, v[148:149]
	s_waitcnt lgkmcnt(1)
	global_store_dwordx4 v[0:1], v[2:5], off sc1
	s_waitcnt lgkmcnt(0)
	global_store_dwordx4 v[0:1], v[6:9], off offset:16 sc1
	s_cbranch_scc0 .LBB0_607

.LBB0_630:
	v_add_u32_e32 v15, s2, v14
	s_waitcnt vmcnt(0)
	v_ashrrev_i32_e32 v40, 7, v15
	v_ashrrev_i32_e32 v41, 31, v40
	v_lshlrev_b64 v[16:17], 12, v[40:41]
	v_lshl_add_u64 v[20:21], v[0:1], 0, v[16:17]
	global_load_dwordx4 v[16:19], v[20:21], off offset:16
	s_nop 0
	global_load_dwordx4 v[20:23], v[20:21], off
	s_nop 0
	global_load_dwordx4 v[24:27], v[4:5], off offset:16
	global_load_dwordx4 v[28:31], v[4:5], off
	global_load_dwordx4 v[32:35], v[2:3], off offset:16
	global_load_dwordx4 v[36:39], v[2:3], off
	v_add_u32_e32 v15, 0x100, v15
	s_addk_i32 s2, 0x200
	s_cmpk_lg_i32 s2, 0x800
	s_waitcnt vmcnt(3)
	v_pk_add_f32 v[24:25], v[24:25], 1.0 op_sel_hi:[1,0]
	s_waitcnt vmcnt(2)
	v_pk_add_f32 v[28:29], v[28:29], 1.0 op_sel_hi:[1,0]
	s_waitcnt vmcnt(1)
	v_pk_fma_f32 v[24:25], v[16:17], v[24:25], v[32:33]
	s_waitcnt vmcnt(0)
	v_pk_fma_f32 v[20:21], v[20:21], v[28:29], v[36:37]
	v_pk_add_f32 v[28:29], v[30:31], 1.0 op_sel_hi:[1,0]
	v_pk_add_f32 v[16:17], v[26:27], 1.0 op_sel_hi:[1,0]
	v_pk_fma_f32 v[22:23], v[22:23], v[28:29], v[38:39]
	v_pk_fma_f32 v[26:27], v[18:19], v[16:17], v[34:35]
	v_cvt_pk_bf16_f32 v16, v20, v21
	v_lshlrev_b64 v[20:21], 11, v[40:41]
	v_ashrrev_i32_e32 v40, 7, v15
	v_cvt_pk_bf16_f32 v17, v22, v23
	v_cvt_pk_bf16_f32 v18, v24, v25
	v_cvt_pk_bf16_f32 v19, v26, v27
	v_lshl_add_u64 v[20:21], v[6:7], 0, v[20:21]
	v_ashrrev_i32_e32 v41, 31, v40
	global_store_dwordx4 v[20:21], v[16:19], off sc1
	s_nop 1
	v_lshlrev_b64 v[16:17], 12, v[40:41]
	v_lshl_add_u64 v[20:21], v[0:1], 0, v[16:17]
	global_load_dwordx4 v[16:19], v[20:21], off offset:16
	s_nop 0
	global_load_dwordx4 v[20:23], v[20:21], off
	s_nop 0
	global_load_dwordx4 v[24:27], v[4:5], off offset:16
	global_load_dwordx4 v[28:31], v[4:5], off
	global_load_dwordx4 v[32:35], v[2:3], off offset:16
	global_load_dwordx4 v[36:39], v[2:3], off
	s_waitcnt vmcnt(3)
	v_pk_add_f32 v[24:25], v[24:25], 1.0 op_sel_hi:[1,0]
	s_waitcnt vmcnt(2)
	v_pk_add_f32 v[28:29], v[28:29], 1.0 op_sel_hi:[1,0]
	s_waitcnt vmcnt(1)
	v_pk_fma_f32 v[24:25], v[16:17], v[24:25], v[32:33]
	s_waitcnt vmcnt(0)
	v_pk_fma_f32 v[20:21], v[20:21], v[28:29], v[36:37]
	v_pk_add_f32 v[28:29], v[30:31], 1.0 op_sel_hi:[1,0]
	v_pk_add_f32 v[16:17], v[26:27], 1.0 op_sel_hi:[1,0]
	v_pk_fma_f32 v[22:23], v[22:23], v[28:29], v[38:39]
	v_pk_fma_f32 v[26:27], v[18:19], v[16:17], v[34:35]
	v_cvt_pk_bf16_f32 v16, v20, v21
	v_lshlrev_b64 v[20:21], 11, v[40:41]
	v_cvt_pk_bf16_f32 v17, v22, v23
	v_cvt_pk_bf16_f32 v18, v24, v25
	v_cvt_pk_bf16_f32 v19, v26, v27
	v_lshl_add_u64 v[20:21], v[6:7], 0, v[20:21]
	global_store_dwordx4 v[20:21], v[16:19], off sc1
	s_cbranch_scc1 .LBB0_630
	s_mov_b64 s[14:15], 0
.LBB0_632:
	s_and_b64 vcc, exec, s[14:15]
	s_cbranch_vccz .LBB0_634
	s_load_dwordx2 s[14:15], s[4:5], 0x60
	s_lshl_b32 s2, s84, 12
	s_add_i32 s26, s2, 0xfeeb0000
	s_lshl_b64 s[16:17], s[26:27], 2
	v_lshl_add_u64 v[24:25], s[26:27], 1, v[12:13]
	s_waitcnt lgkmcnt(0)
	s_add_u32 s14, s14, s16
	s_addc_u32 s15, s15, s17
	v_lshl_add_u64 v[20:21], v[10:11], 2, s[14:15]
	global_load_dwordx4 v[0:3], v[20:21], off
	global_load_dwordx4 v[4:7], v[20:21], off offset:16
	global_load_dwordx4 v[16:19], v[20:21], off offset:32
	s_nop 0
	global_load_dwordx4 v[20:23], v[20:21], off offset:48
	s_waitcnt vmcnt(0)
	v_cvt_pk_bf16_f32 v0, v0, v1
	v_cvt_pk_bf16_f32 v1, v2, v3
	v_cvt_pk_bf16_f32 v2, v4, v5
	v_cvt_pk_bf16_f32 v3, v6, v7
	v_cvt_pk_bf16_f32 v4, v16, v17
	v_cvt_pk_bf16_f32 v5, v18, v19
	v_cvt_pk_bf16_f32 v6, v20, v21
	v_cvt_pk_bf16_f32 v7, v22, v23
	global_store_dwordx4 v[24:25], v[0:3], off sc1
	global_store_dwordx4 v[24:25], v[4:7], off offset:16 sc1

.LBB0_635:
	s_andn2_b64 vcc, exec, s[14:15]
	s_cbranch_vccnz .LBB0_637
	s_add_i32 s2, s84, 0xffffeec0
	s_cmp_gt_u32 s2, 7
	s_cselect_b32 s22, 64, 0
	s_add_i32 s16, s84, 0xffffeeb8
	s_load_dwordx2 s[14:15], s[4:5], 0xc0
	s_cmp_lt_u32 s2, 8
	s_cselect_b32 s2, s2, s16
	s_lshl_b32 s20, s2, 6
	v_mov_b32_e32 v15, v254
	s_ashr_i32 s21, s20, 31
	s_lshl_b64 s[16:17], s[20:21], 2
	v_ashrrev_i32_e32 v16, 4, v15
	s_waitcnt lgkmcnt(0)
	s_add_u32 s14, s14, s16
	v_lshlrev_b32_e32 v18, 4, v15
	v_add_u32_e32 v6, s22, v16
	s_addc_u32 s15, s15, s17
	v_and_b32_e32 v0, 0xf0, v18
	v_mov_b32_e32 v1, v149
	v_ashrrev_i32_e32 v7, 31, v6
	v_lshl_add_u64 v[4:5], s[14:15], 0, v[0:1]
	v_lshlrev_b64 v[2:3], 11, v[6:7]
	v_lshl_add_u64 v[2:3], v[4:5], 0, v[2:3]
	s_waitcnt vmcnt(0)
	s_barrier
	v_mad_u64_u32 v[16:17], s[14:15], v16, s93, v[0:1]
	global_load_dwordx4 v[0:3], v[2:3], off
	v_add_u32_e32 v7, 0x1040, v16
	v_and_b32_e32 v25, 48, v18
	v_ashrrev_i32_e32 v24, 2, v15
	s_lshl_b32 s26, s22, 1
	s_waitcnt vmcnt(0)
	ds_write2_b32 v16, v0, v1 offset1:1
	ds_write2_b32 v16, v2, v3 offset0:2 offset1:3
	v_add_u32_e32 v0, 16, v6
	v_ashrrev_i32_e32 v1, 31, v0
	v_lshlrev_b64 v[0:1], 11, v[0:1]
	v_lshl_add_u64 v[0:1], v[4:5], 0, v[0:1]
	global_load_dwordx4 v[0:3], v[0:1], off
	s_waitcnt vmcnt(0)
	ds_write2_b32 v7, v0, v1 offset1:1
	v_add_u32_e32 v0, 0x1048, v16
	ds_write2_b32 v0, v2, v3 offset1:1
	v_add_u32_e32 v0, 32, v6
	v_ashrrev_i32_e32 v1, 31, v0
	v_lshlrev_b64 v[0:1], 11, v[0:1]
	v_lshl_add_u64 v[0:1], v[4:5], 0, v[0:1]
	global_load_dwordx4 v[0:3], v[0:1], off
	v_add_u32_e32 v7, 0x2080, v16
	s_waitcnt vmcnt(0)
	ds_write2_b32 v7, v0, v1 offset1:1
	v_add_u32_e32 v0, 0x2088, v16
	ds_write2_b32 v0, v2, v3 offset1:1
	v_add_u32_e32 v0, 48, v6
	v_ashrrev_i32_e32 v1, 31, v0
	v_lshlrev_b64 v[0:1], 11, v[0:1]
	v_lshl_add_u64 v[0:1], v[4:5], 0, v[0:1]
	global_load_dwordx4 v[0:3], v[0:1], off
	v_add_u32_e32 v4, 0x30c0, v16
	s_waitcnt vmcnt(0)
	ds_write2_b32 v4, v0, v1 offset1:1
	v_add_u32_e32 v0, 0x30c8, v16
	ds_write2_b32 v0, v2, v3 offset1:1
	v_and_b32_e32 v0, -4, v15
	v_mul_u32_u24_e32 v1, 0x41, v25
	v_lshl_add_u32 v2, v1, 2, v0
	s_waitcnt lgkmcnt(0)
	s_barrier
	ds_read2_b32 v[4:5], v2 offset1:65
	v_add_u32_e32 v3, 0x800, v2
	ds_read2_b32 v[16:17], v3 offset0:8 offset1:73
	ds_read2_b32 v[0:1], v2 offset0:130 offset1:195
	ds_read2_b32 v[18:19], v3 offset0:138 offset1:203
	v_add_u32_e32 v3, 0x400, v2
	ds_read2_b32 v[6:7], v3 offset0:4 offset1:69
	v_add_u32_e32 v15, 0xc00, v2
	s_waitcnt lgkmcnt(2)
	v_cvt_pk_bf16_f32 v1, v0, v1
	v_cvt_pk_bf16_f32 v0, v4, v5
	v_cvt_pk_bf16_f32 v4, v16, v17
	v_add_u32_e32 v16, s20, v24
	ds_read2_b32 v[20:21], v15 offset0:12 offset1:77
	ds_read2_b32 v[2:3], v3 offset0:134 offset1:199
	ds_read2_b32 v[22:23], v15 offset0:142 offset1:207
	v_ashrrev_i32_e32 v17, 31, v16
	v_lshlrev_b64 v[16:17], 8, v[16:17]
	v_lshl_add_u64 v[16:17], s[10:11], 0, v[16:17]
	s_waitcnt lgkmcnt(4)
	v_cvt_pk_bf16_f32 v5, v18, v19
	v_lshl_add_u64 v[16:17], v[16:17], 0, s[26:27]
	v_lshlrev_b32_e32 v18, 1, v25
	v_mov_b32_e32 v19, v149
	s_waitcnt lgkmcnt(1)
	v_cvt_pk_bf16_f32 v3, v2, v3
	v_cvt_pk_bf16_f32 v2, v6, v7
	v_lshl_add_u64 v[16:17], v[16:17], 0, v[18:19]
	s_waitcnt lgkmcnt(0)
	v_cvt_pk_bf16_f32 v7, v22, v23
	v_cvt_pk_bf16_f32 v6, v20, v21
	global_store_dwordx4 v[16:17], v[0:3], off sc1
	global_store_dwordx4 v[16:17], v[4:7], off offset:16 sc1

.LBB0_638:
	s_andn2_b64 vcc, exec, s[14:15]
	s_cbranch_vccnz .LBB0_640
	s_load_dwordx2 s[14:15], s[4:5], 0xa0
	s_add_i32 s2, s84, 0xffffeed0
	s_lshr_b32 s26, s2, 3
	s_lshl_b64 s[16:17], s[26:27], 17
	v_mov_b32_e32 v15, v254
	s_waitcnt lgkmcnt(0)
	s_add_u32 s2, s14, s16
	s_addc_u32 s16, s15, s17
	s_lshl_b64 s[14:15], s[26:27], 16
	s_add_u32 s20, s40, s14
	s_addc_u32 s21, s41, s15
	s_lshl_b32 s14, s84, 6
	s_and_b32 s17, s14, 0x1c0
	s_lshl_b32 s14, s17, 2
	s_add_u32 s14, s2, s14
	v_ashrrev_i32_e32 v0, 4, v15
	v_lshlrev_b32_e32 v16, 4, v15
	s_addc_u32 s15, s16, 0
	v_and_b32_e32 v2, 0xf0, v16
	v_mov_b32_e32 v3, v149
	v_ashrrev_i32_e32 v1, 31, v0
	v_lshl_add_u64 v[4:5], s[14:15], 0, v[2:3]
	v_lshlrev_b64 v[6:7], 11, v[0:1]
	v_lshl_add_u64 v[4:5], v[4:5], 0, v[6:7]
	s_waitcnt vmcnt(0)
	s_barrier
	v_mad_u64_u32 v[6:7], s[14:15], v0, s93, v[2:3]
	global_load_dwordx4 v[0:3], v[4:5], off
	s_mov_b32 s2, 0x8000
	v_add_u32_e32 v7, 0x1040, v6
	v_and_b32_e32 v25, 48, v16
	v_ashrrev_i32_e32 v24, 2, v15
	s_waitcnt vmcnt(0)
	ds_write2_b32 v6, v0, v1 offset1:1
	ds_write2_b32 v6, v2, v3 offset0:2 offset1:3
	v_add_co_u32_e32 v0, vcc, s2, v4
	s_mov_b32 s2, 0x10000
	s_nop 0
	v_addc_co_u32_e32 v1, vcc, 0, v5, vcc
	global_load_dwordx4 v[0:3], v[0:1], off
	s_waitcnt vmcnt(0)
	ds_write2_b32 v7, v0, v1 offset1:1
	v_add_u32_e32 v0, 0x1048, v6
	ds_write2_b32 v0, v2, v3 offset1:1
	v_add_co_u32_e32 v0, vcc, s2, v4
	v_add_u32_e32 v7, 0x2080, v6
	s_nop 0
	v_addc_co_u32_e32 v1, vcc, 0, v5, vcc
	global_load_dwordx4 v[0:3], v[0:1], off
	s_mov_b32 s2, 0x18000
	s_waitcnt vmcnt(0)
	ds_write2_b32 v7, v0, v1 offset1:1
	v_add_u32_e32 v0, 0x2088, v6
	ds_write2_b32 v0, v2, v3 offset1:1
	v_add_co_u32_e32 v0, vcc, s2, v4
	v_add_u32_e32 v7, 0x30c0, v6
	s_nop 0
	v_addc_co_u32_e32 v1, vcc, 0, v5, vcc
	global_load_dwordx4 v[0:3], v[0:1], off
	s_waitcnt vmcnt(0)
	ds_write2_b32 v7, v0, v1 offset1:1
	v_add_u32_e32 v0, 0x30c8, v6
	ds_write2_b32 v0, v2, v3 offset1:1
	v_and_b32_e32 v0, -4, v15
	v_mul_u32_u24_e32 v1, 0x41, v25
	v_lshl_add_u32 v2, v1, 2, v0
	s_waitcnt lgkmcnt(0)
	s_barrier
	ds_read2_b32 v[4:5], v2 offset1:65
	v_add_u32_e32 v3, 0x800, v2
	ds_read2_b32 v[16:17], v3 offset0:8 offset1:73
	ds_read2_b32 v[0:1], v2 offset0:130 offset1:195
	ds_read2_b32 v[18:19], v3 offset0:138 offset1:203
	v_add_u32_e32 v3, 0x400, v2
	ds_read2_b32 v[6:7], v3 offset0:4 offset1:69
	v_add_u32_e32 v15, 0xc00, v2
	ds_read2_b32 v[20:21], v15 offset0:12 offset1:77
	ds_read2_b32 v[2:3], v3 offset0:134 offset1:199
	ds_read2_b32 v[22:23], v15 offset0:142 offset1:207
	s_waitcnt lgkmcnt(5)
	v_cvt_pk_bf16_f32 v1, v0, v1
	v_cvt_pk_bf16_f32 v0, v4, v5
	v_cvt_pk_bf16_f32 v4, v16, v17
	v_add_u32_e32 v16, s17, v24
	v_ashrrev_i32_e32 v17, 31, v16
	v_lshlrev_b64 v[16:17], 7, v[16:17]
	s_waitcnt lgkmcnt(4)
	v_cvt_pk_bf16_f32 v5, v18, v19
	v_lshl_add_u64 v[16:17], s[20:21], 0, v[16:17]
	v_lshlrev_b32_e32 v18, 1, v25
	v_mov_b32_e32 v19, v149
	s_waitcnt lgkmcnt(1)
	v_cvt_pk_bf16_f32 v3, v2, v3
	v_cvt_pk_bf16_f32 v2, v6, v7
	v_lshl_add_u64 v[16:17], v[16:17], 0, v[18:19]
	s_waitcnt lgkmcnt(0)
	v_cvt_pk_bf16_f32 v7, v22, v23
	v_cvt_pk_bf16_f32 v6, v20, v21
	global_store_dwordx4 v[16:17], v[0:3], off sc1
	global_store_dwordx4 v[16:17], v[4:7], off offset:16 sc1

.LBB0_641:
	s_andn2_b64 vcc, exec, s[14:15]
	s_cbranch_vccnz .LBB0_643
	s_load_dwordx2 s[14:15], s[4:5], 0x90
	s_add_i32 s2, s84, 0xffffeee0
	s_lshr_b32 s26, s2, 3
	s_lshl_b64 s[16:17], s[26:27], 17
	v_mov_b32_e32 v15, v254
	s_waitcnt lgkmcnt(0)
	s_add_u32 s2, s14, s16
	s_addc_u32 s16, s15, s17
	s_lshl_b64 s[14:15], s[26:27], 16
	s_add_u32 s20, s44, s14
	s_addc_u32 s21, s45, s15
	s_lshl_b32 s14, s84, 6
	s_and_b32 s17, s14, 0x1c0
	s_lshl_b32 s14, s17, 2
	s_add_u32 s14, s2, s14
	v_ashrrev_i32_e32 v0, 4, v15
	v_lshlrev_b32_e32 v16, 4, v15
	s_addc_u32 s15, s16, 0
	v_and_b32_e32 v2, 0xf0, v16
	v_mov_b32_e32 v3, v149
	v_ashrrev_i32_e32 v1, 31, v0
	v_lshl_add_u64 v[4:5], s[14:15], 0, v[2:3]
	v_lshlrev_b64 v[6:7], 11, v[0:1]
	v_lshl_add_u64 v[4:5], v[4:5], 0, v[6:7]
	s_waitcnt vmcnt(0)
	s_barrier
	v_mad_u64_u32 v[6:7], s[14:15], v0, s93, v[2:3]
	global_load_dwordx4 v[0:3], v[4:5], off
	s_mov_b32 s2, 0x8000
	v_add_u32_e32 v7, 0x1040, v6
	v_and_b32_e32 v25, 48, v16
	v_ashrrev_i32_e32 v24, 2, v15
	s_waitcnt vmcnt(0)
	ds_write2_b32 v6, v0, v1 offset1:1
	ds_write2_b32 v6, v2, v3 offset0:2 offset1:3
	v_add_co_u32_e32 v0, vcc, s2, v4
	s_mov_b32 s2, 0x10000
	s_nop 0
	v_addc_co_u32_e32 v1, vcc, 0, v5, vcc
	global_load_dwordx4 v[0:3], v[0:1], off
	s_waitcnt vmcnt(0)
	ds_write2_b32 v7, v0, v1 offset1:1
	v_add_u32_e32 v0, 0x1048, v6
	ds_write2_b32 v0, v2, v3 offset1:1
	v_add_co_u32_e32 v0, vcc, s2, v4
	v_add_u32_e32 v7, 0x2080, v6
	s_nop 0
	v_addc_co_u32_e32 v1, vcc, 0, v5, vcc
	global_load_dwordx4 v[0:3], v[0:1], off
	s_mov_b32 s2, 0x18000
	s_waitcnt vmcnt(0)
	ds_write2_b32 v7, v0, v1 offset1:1
	v_add_u32_e32 v0, 0x2088, v6
	ds_write2_b32 v0, v2, v3 offset1:1
	v_add_co_u32_e32 v0, vcc, s2, v4
	v_add_u32_e32 v7, 0x30c0, v6
	s_nop 0
	v_addc_co_u32_e32 v1, vcc, 0, v5, vcc
	global_load_dwordx4 v[0:3], v[0:1], off
	s_waitcnt vmcnt(0)
	ds_write2_b32 v7, v0, v1 offset1:1
	v_add_u32_e32 v0, 0x30c8, v6
	ds_write2_b32 v0, v2, v3 offset1:1
	v_and_b32_e32 v0, -4, v15
	v_mul_u32_u24_e32 v1, 0x41, v25
	v_lshl_add_u32 v2, v1, 2, v0
	s_waitcnt lgkmcnt(0)
	s_barrier
	ds_read2_b32 v[4:5], v2 offset1:65
	v_add_u32_e32 v3, 0x800, v2
	ds_read2_b32 v[16:17], v3 offset0:8 offset1:73
	ds_read2_b32 v[0:1], v2 offset0:130 offset1:195
	ds_read2_b32 v[18:19], v3 offset0:138 offset1:203
	v_add_u32_e32 v3, 0x400, v2
	ds_read2_b32 v[6:7], v3 offset0:4 offset1:69
	v_add_u32_e32 v15, 0xc00, v2
	ds_read2_b32 v[20:21], v15 offset0:12 offset1:77
	ds_read2_b32 v[2:3], v3 offset0:134 offset1:199
	ds_read2_b32 v[22:23], v15 offset0:142 offset1:207
	s_waitcnt lgkmcnt(5)
	v_cvt_pk_bf16_f32 v1, v0, v1
	v_cvt_pk_bf16_f32 v0, v4, v5
	v_cvt_pk_bf16_f32 v4, v16, v17
	v_add_u32_e32 v16, s17, v24
	v_ashrrev_i32_e32 v17, 31, v16
	v_lshlrev_b64 v[16:17], 7, v[16:17]
	s_waitcnt lgkmcnt(4)
	v_cvt_pk_bf16_f32 v5, v18, v19
	v_lshl_add_u64 v[16:17], s[20:21], 0, v[16:17]
	v_lshlrev_b32_e32 v18, 1, v25
	v_mov_b32_e32 v19, v149
	s_waitcnt lgkmcnt(1)
	v_cvt_pk_bf16_f32 v3, v2, v3
	v_cvt_pk_bf16_f32 v2, v6, v7
	v_lshl_add_u64 v[16:17], v[16:17], 0, v[18:19]
	s_waitcnt lgkmcnt(0)
	v_cvt_pk_bf16_f32 v7, v22, v23
	v_cvt_pk_bf16_f32 v6, v20, v21
	global_store_dwordx4 v[16:17], v[0:3], off sc1
	global_store_dwordx4 v[16:17], v[4:7], off offset:16 sc1

.LBB0_644:
	s_andn2_b64 vcc, exec, s[14:15]
	s_cbranch_vccnz .LBB0_646
	s_load_dwordx2 s[14:15], s[4:5], 0x100
	s_lshl_b32 s2, s84, 2
	s_lshl_b32 s16, s84, 6
	s_add_i32 s2, s2, 0x3cb80
	s_and_b32 s16, s16, 0x3c0
	v_mov_b32_e32 v15, v254
	s_and_b32 s2, s2, 0x3ffc0
	s_lshl_b32 s17, s16, 2
	v_ashrrev_i32_e32 v16, 4, v15
	s_waitcnt lgkmcnt(0)
	s_add_u32 s14, s14, s17
	v_lshlrev_b32_e32 v18, 4, v15
	v_add_u32_e32 v6, s2, v16
	s_addc_u32 s15, s15, 0
	v_and_b32_e32 v0, 0xf0, v18
	v_mov_b32_e32 v1, v149
	v_ashrrev_i32_e32 v7, 31, v6
	v_lshl_add_u64 v[4:5], s[14:15], 0, v[0:1]
	v_lshlrev_b64 v[2:3], 12, v[6:7]
	v_lshl_add_u64 v[2:3], v[4:5], 0, v[2:3]
	s_waitcnt vmcnt(0)
	s_barrier
	v_mad_u64_u32 v[16:17], s[14:15], v16, s93, v[0:1]
	global_load_dwordx4 v[0:3], v[2:3], off
	v_add_u32_e32 v7, 0x1040, v16
	v_and_b32_e32 v25, 48, v18
	v_ashrrev_i32_e32 v24, 2, v15
	s_lshl_b32 s26, s2, 1
	s_waitcnt vmcnt(0)
	ds_write2_b32 v16, v0, v1 offset1:1
	ds_write2_b32 v16, v2, v3 offset0:2 offset1:3
	v_add_u32_e32 v0, 16, v6
	v_ashrrev_i32_e32 v1, 31, v0
	v_lshlrev_b64 v[0:1], 12, v[0:1]
	v_lshl_add_u64 v[0:1], v[4:5], 0, v[0:1]
	global_load_dwordx4 v[0:3], v[0:1], off
	s_waitcnt vmcnt(0)
	ds_write2_b32 v7, v0, v1 offset1:1
	v_add_u32_e32 v0, 0x1048, v16
	ds_write2_b32 v0, v2, v3 offset1:1
	v_add_u32_e32 v0, 32, v6
	v_ashrrev_i32_e32 v1, 31, v0
	v_lshlrev_b64 v[0:1], 12, v[0:1]
	v_lshl_add_u64 v[0:1], v[4:5], 0, v[0:1]
	global_load_dwordx4 v[0:3], v[0:1], off
	v_add_u32_e32 v7, 0x2080, v16
	s_waitcnt vmcnt(0)
	ds_write2_b32 v7, v0, v1 offset1:1
	v_add_u32_e32 v0, 0x2088, v16
	ds_write2_b32 v0, v2, v3 offset1:1
	v_add_u32_e32 v0, 48, v6
	v_ashrrev_i32_e32 v1, 31, v0
	v_lshlrev_b64 v[0:1], 12, v[0:1]
	v_lshl_add_u64 v[0:1], v[4:5], 0, v[0:1]
	global_load_dwordx4 v[0:3], v[0:1], off
	v_add_u32_e32 v4, 0x30c0, v16
	s_waitcnt vmcnt(0)
	ds_write2_b32 v4, v0, v1 offset1:1
	v_add_u32_e32 v0, 0x30c8, v16
	ds_write2_b32 v0, v2, v3 offset1:1
	v_and_b32_e32 v0, -4, v15
	v_mul_u32_u24_e32 v1, 0x41, v25
	v_lshl_add_u32 v2, v1, 2, v0
	s_waitcnt lgkmcnt(0)
	s_barrier
	ds_read2_b32 v[4:5], v2 offset1:65
	v_add_u32_e32 v3, 0x800, v2
	ds_read2_b32 v[16:17], v3 offset0:8 offset1:73
	ds_read2_b32 v[0:1], v2 offset0:130 offset1:195
	ds_read2_b32 v[18:19], v3 offset0:138 offset1:203
	v_add_u32_e32 v3, 0x400, v2
	ds_read2_b32 v[6:7], v3 offset0:4 offset1:69
	v_add_u32_e32 v15, 0xc00, v2
	s_waitcnt lgkmcnt(2)
	v_cvt_pk_bf16_f32 v1, v0, v1
	v_cvt_pk_bf16_f32 v0, v4, v5
	v_cvt_pk_bf16_f32 v4, v16, v17
	v_add_u32_e32 v16, s16, v24
	ds_read2_b32 v[20:21], v15 offset0:12 offset1:77
	ds_read2_b32 v[2:3], v3 offset0:134 offset1:199
	ds_read2_b32 v[22:23], v15 offset0:142 offset1:207
	v_ashrrev_i32_e32 v17, 31, v16
	v_lshlrev_b64 v[16:17], 13, v[16:17]
	v_lshl_add_u64 v[16:17], s[12:13], 0, v[16:17]
	s_waitcnt lgkmcnt(4)
	v_cvt_pk_bf16_f32 v5, v18, v19
	v_lshl_add_u64 v[16:17], v[16:17], 0, s[26:27]
	v_lshlrev_b32_e32 v18, 1, v25
	v_mov_b32_e32 v19, v149
	s_waitcnt lgkmcnt(1)
	v_cvt_pk_bf16_f32 v3, v2, v3
	v_cvt_pk_bf16_f32 v2, v6, v7
	v_lshl_add_u64 v[16:17], v[16:17], 0, v[18:19]
	s_waitcnt lgkmcnt(0)
	v_cvt_pk_bf16_f32 v7, v22, v23
	v_cvt_pk_bf16_f32 v6, v20, v21
	global_store_dwordx4 v[16:17], v[0:3], off sc1
	global_store_dwordx4 v[16:17], v[4:7], off offset:16 sc1

.LBB0_647:
	s_andn2_b64 vcc, exec, s[14:15]
	s_cbranch_vccnz .LBB0_649
	s_load_dwordx2 s[14:15], s[4:5], 0xf8
	s_add_i32 s2, s84, 0xfffff6e0
	s_and_b32 s16, s2, 0xffc0
	s_lshl_b32 s2, s2, 6
	s_and_b32 s2, s2, 0xfc0
	v_mov_b32_e32 v15, v254
	s_lshl_b32 s17, s2, 2
	v_ashrrev_i32_e32 v16, 4, v15
	s_waitcnt lgkmcnt(0)
	s_add_u32 s14, s14, s17
	v_lshlrev_b32_e32 v18, 4, v15
	v_add_u32_e32 v6, s16, v16
	s_addc_u32 s15, s15, 0
	v_and_b32_e32 v0, 0xf0, v18
	v_mov_b32_e32 v1, v149
	v_ashrrev_i32_e32 v7, 31, v6
	v_lshl_add_u64 v[4:5], s[14:15], 0, v[0:1]
	v_lshlrev_b64 v[2:3], 14, v[6:7]
	v_lshl_add_u64 v[2:3], v[4:5], 0, v[2:3]
	s_waitcnt vmcnt(0)
	s_barrier
	v_mad_u64_u32 v[16:17], s[14:15], v16, s93, v[0:1]
	global_load_dwordx4 v[0:3], v[2:3], off
	v_add_u32_e32 v7, 0x1040, v16
	v_and_b32_e32 v25, 48, v18
	v_ashrrev_i32_e32 v24, 2, v15
	s_lshl_b32 s26, s16, 1
	s_waitcnt vmcnt(0)
	ds_write2_b32 v16, v0, v1 offset1:1
	ds_write2_b32 v16, v2, v3 offset0:2 offset1:3
	v_add_u32_e32 v0, 16, v6
	v_ashrrev_i32_e32 v1, 31, v0
	v_lshlrev_b64 v[0:1], 14, v[0:1]
	v_lshl_add_u64 v[0:1], v[4:5], 0, v[0:1]
	global_load_dwordx4 v[0:3], v[0:1], off
	s_waitcnt vmcnt(0)
	ds_write2_b32 v7, v0, v1 offset1:1
	v_add_u32_e32 v0, 0x1048, v16
	ds_write2_b32 v0, v2, v3 offset1:1
	v_add_u32_e32 v0, 32, v6
	v_ashrrev_i32_e32 v1, 31, v0
	v_lshlrev_b64 v[0:1], 14, v[0:1]
	v_lshl_add_u64 v[0:1], v[4:5], 0, v[0:1]
	global_load_dwordx4 v[0:3], v[0:1], off
	v_add_u32_e32 v7, 0x2080, v16
	s_waitcnt vmcnt(0)
	ds_write2_b32 v7, v0, v1 offset1:1
	v_add_u32_e32 v0, 0x2088, v16
	ds_write2_b32 v0, v2, v3 offset1:1
	v_add_u32_e32 v0, 48, v6
	v_ashrrev_i32_e32 v1, 31, v0
	v_lshlrev_b64 v[0:1], 14, v[0:1]
	v_lshl_add_u64 v[0:1], v[4:5], 0, v[0:1]
	global_load_dwordx4 v[0:3], v[0:1], off
	v_add_u32_e32 v4, 0x30c0, v16
	s_waitcnt vmcnt(0)
	ds_write2_b32 v4, v0, v1 offset1:1
	v_add_u32_e32 v0, 0x30c8, v16
	ds_write2_b32 v0, v2, v3 offset1:1
	v_and_b32_e32 v0, -4, v15
	v_mul_u32_u24_e32 v1, 0x41, v25
	v_lshl_add_u32 v2, v1, 2, v0
	s_waitcnt lgkmcnt(0)
	s_barrier
	ds_read2_b32 v[4:5], v2 offset1:65
	v_add_u32_e32 v3, 0x800, v2
	ds_read2_b32 v[16:17], v3 offset0:8 offset1:73
	ds_read2_b32 v[0:1], v2 offset0:130 offset1:195
	ds_read2_b32 v[18:19], v3 offset0:138 offset1:203
	v_add_u32_e32 v3, 0x400, v2
	ds_read2_b32 v[6:7], v3 offset0:4 offset1:69
	v_add_u32_e32 v15, 0xc00, v2
	s_waitcnt lgkmcnt(2)
	v_cvt_pk_bf16_f32 v1, v0, v1
	v_cvt_pk_bf16_f32 v0, v4, v5
	v_cvt_pk_bf16_f32 v4, v16, v17
	v_add_u32_e32 v16, s2, v24
	ds_read2_b32 v[20:21], v15 offset0:12 offset1:77
	ds_read2_b32 v[2:3], v3 offset0:134 offset1:199
	ds_read2_b32 v[22:23], v15 offset0:142 offset1:207
	v_ashrrev_i32_e32 v17, 31, v16
	v_lshlrev_b64 v[16:17], 11, v[16:17]
	v_lshl_add_u64 v[16:17], s[8:9], 0, v[16:17]
	s_waitcnt lgkmcnt(4)
	v_cvt_pk_bf16_f32 v5, v18, v19
	v_lshl_add_u64 v[16:17], v[16:17], 0, s[26:27]
	v_lshlrev_b32_e32 v18, 1, v25
	v_mov_b32_e32 v19, v149
	s_waitcnt lgkmcnt(1)
	v_cvt_pk_bf16_f32 v3, v2, v3
	v_cvt_pk_bf16_f32 v2, v6, v7
	v_lshl_add_u64 v[16:17], v[16:17], 0, v[18:19]
	s_waitcnt lgkmcnt(0)
	v_cvt_pk_bf16_f32 v7, v22, v23
	v_cvt_pk_bf16_f32 v6, v20, v21
	global_store_dwordx4 v[16:17], v[0:3], off sc1
	global_store_dwordx4 v[16:17], v[4:7], off offset:16 sc1

.LBB0_650:
	s_andn2_b64 vcc, exec, s[14:15]
	s_cbranch_vccnz .LBB0_652
	s_load_dwordx2 s[14:15], s[4:5], 0xe0
	s_lshl_b32 s2, s84, 2
	s_lshl_b32 s16, s84, 6
	s_addk_i32 s2, 0x380
	s_and_b32 s16, s16, 0x3c0
	v_mov_b32_e32 v15, v254
	s_and_b32 s2, s2, 0x3c0
	s_lshl_b32 s17, s16, 2
	v_ashrrev_i32_e32 v16, 4, v15
	s_waitcnt lgkmcnt(0)
	s_add_u32 s14, s14, s17
	v_lshlrev_b32_e32 v18, 4, v15
	v_add_u32_e32 v6, s2, v16
	s_addc_u32 s15, s15, 0
	v_and_b32_e32 v0, 0xf0, v18
	v_mov_b32_e32 v1, v149
	v_ashrrev_i32_e32 v7, 31, v6
	v_lshl_add_u64 v[4:5], s[14:15], 0, v[0:1]
	v_lshlrev_b64 v[2:3], 12, v[6:7]
	v_lshl_add_u64 v[2:3], v[4:5], 0, v[2:3]
	s_waitcnt vmcnt(0)
	s_barrier
	v_mad_u64_u32 v[16:17], s[14:15], v16, s93, v[0:1]
	global_load_dwordx4 v[0:3], v[2:3], off
	v_add_u32_e32 v7, 0x1040, v16
	v_and_b32_e32 v25, 48, v18
	v_ashrrev_i32_e32 v24, 2, v15
	s_lshl_b32 s26, s2, 1
	s_waitcnt vmcnt(0)
	ds_write2_b32 v16, v0, v1 offset1:1
	ds_write2_b32 v16, v2, v3 offset0:2 offset1:3
	v_add_u32_e32 v0, 16, v6
	v_ashrrev_i32_e32 v1, 31, v0
	v_lshlrev_b64 v[0:1], 12, v[0:1]
	v_lshl_add_u64 v[0:1], v[4:5], 0, v[0:1]
	global_load_dwordx4 v[0:3], v[0:1], off
	s_waitcnt vmcnt(0)
	ds_write2_b32 v7, v0, v1 offset1:1
	v_add_u32_e32 v0, 0x1048, v16
	ds_write2_b32 v0, v2, v3 offset1:1
	v_add_u32_e32 v0, 32, v6
	v_ashrrev_i32_e32 v1, 31, v0
	v_lshlrev_b64 v[0:1], 12, v[0:1]
	v_lshl_add_u64 v[0:1], v[4:5], 0, v[0:1]
	global_load_dwordx4 v[0:3], v[0:1], off
	v_add_u32_e32 v7, 0x2080, v16
	s_waitcnt vmcnt(0)
	ds_write2_b32 v7, v0, v1 offset1:1
	v_add_u32_e32 v0, 0x2088, v16
	ds_write2_b32 v0, v2, v3 offset1:1
	v_add_u32_e32 v0, 48, v6
	v_ashrrev_i32_e32 v1, 31, v0
	v_lshlrev_b64 v[0:1], 12, v[0:1]
	v_lshl_add_u64 v[0:1], v[4:5], 0, v[0:1]
	global_load_dwordx4 v[0:3], v[0:1], off
	v_add_u32_e32 v4, 0x30c0, v16
	s_waitcnt vmcnt(0)
	ds_write2_b32 v4, v0, v1 offset1:1
	v_add_u32_e32 v0, 0x30c8, v16
	ds_write2_b32 v0, v2, v3 offset1:1
	v_and_b32_e32 v0, -4, v15
	v_mul_u32_u24_e32 v1, 0x41, v25
	v_lshl_add_u32 v2, v1, 2, v0
	s_waitcnt lgkmcnt(0)
	s_barrier
	ds_read2_b32 v[4:5], v2 offset1:65
	v_add_u32_e32 v3, 0x800, v2
	ds_read2_b32 v[16:17], v3 offset0:8 offset1:73
	ds_read2_b32 v[0:1], v2 offset0:130 offset1:195
	ds_read2_b32 v[18:19], v3 offset0:138 offset1:203
	v_add_u32_e32 v3, 0x400, v2
	ds_read2_b32 v[6:7], v3 offset0:4 offset1:69
	v_add_u32_e32 v15, 0xc00, v2
	s_waitcnt lgkmcnt(2)
	v_cvt_pk_bf16_f32 v1, v0, v1
	v_cvt_pk_bf16_f32 v0, v4, v5
	v_cvt_pk_bf16_f32 v4, v16, v17
	v_add_u32_e32 v16, s16, v24
	ds_read2_b32 v[20:21], v15 offset0:12 offset1:77
	ds_read2_b32 v[2:3], v3 offset0:134 offset1:199
	ds_read2_b32 v[22:23], v15 offset0:142 offset1:207
	v_ashrrev_i32_e32 v17, 31, v16
	v_lshlrev_b64 v[16:17], 11, v[16:17]
	v_lshl_add_u64 v[16:17], s[28:29], 0, v[16:17]
	s_waitcnt lgkmcnt(4)
	v_cvt_pk_bf16_f32 v5, v18, v19
	v_lshl_add_u64 v[16:17], v[16:17], 0, s[26:27]
	v_lshlrev_b32_e32 v18, 1, v25
	v_mov_b32_e32 v19, v149
	s_waitcnt lgkmcnt(1)
	v_cvt_pk_bf16_f32 v3, v2, v3
	v_cvt_pk_bf16_f32 v2, v6, v7
	v_lshl_add_u64 v[16:17], v[16:17], 0, v[18:19]
	s_waitcnt lgkmcnt(0)
	v_cvt_pk_bf16_f32 v7, v22, v23
	v_cvt_pk_bf16_f32 v6, v20, v21
	global_store_dwordx4 v[16:17], v[0:3], off sc1
	global_store_dwordx4 v[16:17], v[4:7], off offset:16 sc1

.LBB0_653:
	s_andn2_b64 vcc, exec, s[14:15]
	s_cbranch_vccnz .LBB0_655
	s_load_dwordx2 s[14:15], s[4:5], 0xd8
	s_add_i32 s2, s84, 0xfffff960
	s_lshr_b32 s26, s2, 7
	s_lshl_b64 s[16:17], s[26:27], 21
	v_mov_b32_e32 v15, v254
	s_waitcnt lgkmcnt(0)
	s_add_u32 s16, s14, s16
	s_addc_u32 s17, s15, s17
	s_lshl_b64 s[14:15], s[26:27], 20
	s_add_u32 s20, s82, s14
	s_addc_u32 s21, s83, s15
	s_lshl_b32 s14, s84, 6
	s_lshl_b32 s2, s2, 2
	s_and_b32 s22, s14, 0x3c0
	s_and_b32 s2, s2, 0x1c0
	s_lshl_b32 s14, s22, 2
	v_ashrrev_i32_e32 v16, 4, v15
	s_add_u32 s14, s16, s14
	v_lshlrev_b32_e32 v18, 4, v15
	v_add_u32_e32 v6, s2, v16
	s_addc_u32 s15, s17, 0
	v_and_b32_e32 v0, 0xf0, v18
	v_mov_b32_e32 v1, v149
	v_ashrrev_i32_e32 v7, 31, v6
	v_lshl_add_u64 v[4:5], s[14:15], 0, v[0:1]
	v_lshlrev_b64 v[2:3], 12, v[6:7]
	v_lshl_add_u64 v[2:3], v[4:5], 0, v[2:3]
	s_waitcnt vmcnt(0)
	s_barrier
	v_mad_u64_u32 v[16:17], s[14:15], v16, s93, v[0:1]
	global_load_dwordx4 v[0:3], v[2:3], off
	v_add_u32_e32 v7, 0x1040, v16
	v_and_b32_e32 v25, 48, v18
	v_ashrrev_i32_e32 v24, 2, v15
	s_lshl_b32 s26, s2, 1
	s_waitcnt vmcnt(0)
	ds_write2_b32 v16, v0, v1 offset1:1
	ds_write2_b32 v16, v2, v3 offset0:2 offset1:3
	v_add_u32_e32 v0, 16, v6
	v_ashrrev_i32_e32 v1, 31, v0
	v_lshlrev_b64 v[0:1], 12, v[0:1]
	v_lshl_add_u64 v[0:1], v[4:5], 0, v[0:1]
	global_load_dwordx4 v[0:3], v[0:1], off
	s_waitcnt vmcnt(0)
	ds_write2_b32 v7, v0, v1 offset1:1
	v_add_u32_e32 v0, 0x1048, v16
	ds_write2_b32 v0, v2, v3 offset1:1
	v_add_u32_e32 v0, 32, v6
	v_ashrrev_i32_e32 v1, 31, v0
	v_lshlrev_b64 v[0:1], 12, v[0:1]
	v_lshl_add_u64 v[0:1], v[4:5], 0, v[0:1]
	global_load_dwordx4 v[0:3], v[0:1], off
	v_add_u32_e32 v7, 0x2080, v16
	s_waitcnt vmcnt(0)
	ds_write2_b32 v7, v0, v1 offset1:1
	v_add_u32_e32 v0, 0x2088, v16
	ds_write2_b32 v0, v2, v3 offset1:1
	v_add_u32_e32 v0, 48, v6
	v_ashrrev_i32_e32 v1, 31, v0
	v_lshlrev_b64 v[0:1], 12, v[0:1]
	v_lshl_add_u64 v[0:1], v[4:5], 0, v[0:1]
	global_load_dwordx4 v[0:3], v[0:1], off
	v_add_u32_e32 v4, 0x30c0, v16
	s_waitcnt vmcnt(0)
	ds_write2_b32 v4, v0, v1 offset1:1
	v_add_u32_e32 v0, 0x30c8, v16
	ds_write2_b32 v0, v2, v3 offset1:1
	v_and_b32_e32 v0, -4, v15
	v_mul_u32_u24_e32 v1, 0x41, v25
	v_lshl_add_u32 v2, v1, 2, v0
	s_waitcnt lgkmcnt(0)
	s_barrier
	ds_read2_b32 v[4:5], v2 offset1:65
	v_add_u32_e32 v3, 0x800, v2
	ds_read2_b32 v[16:17], v3 offset0:8 offset1:73
	ds_read2_b32 v[0:1], v2 offset0:130 offset1:195
	ds_read2_b32 v[18:19], v3 offset0:138 offset1:203
	v_add_u32_e32 v3, 0x400, v2
	ds_read2_b32 v[6:7], v3 offset0:4 offset1:69
	v_add_u32_e32 v15, 0xc00, v2
	s_waitcnt lgkmcnt(2)
	v_cvt_pk_bf16_f32 v1, v0, v1
	v_cvt_pk_bf16_f32 v0, v4, v5
	v_cvt_pk_bf16_f32 v4, v16, v17
	v_add_u32_e32 v16, s22, v24
	ds_read2_b32 v[20:21], v15 offset0:12 offset1:77
	ds_read2_b32 v[2:3], v3 offset0:134 offset1:199
	ds_read2_b32 v[22:23], v15 offset0:142 offset1:207
	v_ashrrev_i32_e32 v17, 31, v16
	v_lshlrev_b64 v[16:17], 10, v[16:17]
	v_lshl_add_u64 v[16:17], s[20:21], 0, v[16:17]
	s_waitcnt lgkmcnt(4)
	v_cvt_pk_bf16_f32 v5, v18, v19
	v_lshl_add_u64 v[16:17], v[16:17], 0, s[26:27]
	v_lshlrev_b32_e32 v18, 1, v25
	v_mov_b32_e32 v19, v149
	s_waitcnt lgkmcnt(1)
	v_cvt_pk_bf16_f32 v3, v2, v3
	v_cvt_pk_bf16_f32 v2, v6, v7
	v_lshl_add_u64 v[16:17], v[16:17], 0, v[18:19]
	s_waitcnt lgkmcnt(0)
	v_cvt_pk_bf16_f32 v7, v22, v23
	v_cvt_pk_bf16_f32 v6, v20, v21
	global_store_dwordx4 v[16:17], v[0:3], off sc1
	global_store_dwordx4 v[16:17], v[4:7], off offset:16 sc1

.LBB0_656:
	s_mul_hi_i32 s2, s84, 0x4d4873ed
	s_lshr_b32 s16, s2, 31
	s_ashr_i32 s2, s2, 5
	s_add_i32 s2, s2, s16
	s_load_dwordx2 s[14:15], s[4:5], 0x48
	s_lshl_b32 s20, s2, 6
	s_mulk_i32 s2, 0x6a
	s_sub_i32 s2, s84, s2
	s_lshl_b32 s22, s2, 6
	s_ashr_i32 s23, s22, 31
	v_mov_b32_e32 v15, v254
	s_lshl_b64 s[16:17], s[22:23], 2
	s_waitcnt lgkmcnt(0)
	s_add_u32 s14, s14, s16
	v_lshlrev_b32_e32 v16, 4, v15
	v_ashrrev_i32_e32 v6, 4, v15
	s_addc_u32 s15, s15, s17
	v_and_b32_e32 v0, 0xf0, v16
	v_mov_b32_e32 v1, v149
	v_lshl_add_u64 v[4:5], s[14:15], 0, v[0:1]
	v_add_u32_e32 v17, s20, v6
	s_movk_i32 s2, 0x6a00
	v_mad_i64_i32 v[2:3], s[14:15], v17, s2, v[4:5]
	s_waitcnt vmcnt(0)
	s_barrier
	v_mad_u64_u32 v[6:7], s[14:15], v6, s93, v[0:1]
	global_load_dwordx4 v[0:3], v[2:3], off
	v_add_u32_e32 v7, 0x1040, v6
	v_and_b32_e32 v25, 48, v16
	v_ashrrev_i32_e32 v24, 2, v15
	s_ashr_i32 s21, s20, 31
	s_waitcnt vmcnt(0)
	ds_write2_b32 v6, v0, v1 offset1:1
	ds_write2_b32 v6, v2, v3 offset0:2 offset1:3
	v_add_u32_e32 v0, 16, v17
	v_mad_i64_i32 v[0:1], s[14:15], v0, s2, v[4:5]
	global_load_dwordx4 v[0:3], v[0:1], off
	s_waitcnt vmcnt(0)
	ds_write2_b32 v7, v0, v1 offset1:1
	v_add_u32_e32 v0, 0x1048, v6
	ds_write2_b32 v0, v2, v3 offset1:1
	v_add_u32_e32 v0, 32, v17
	v_mad_i64_i32 v[0:1], s[14:15], v0, s2, v[4:5]
	global_load_dwordx4 v[0:3], v[0:1], off
	v_add_u32_e32 v7, 0x2080, v6
	s_waitcnt vmcnt(0)
	ds_write2_b32 v7, v0, v1 offset1:1
	v_add_u32_e32 v0, 0x2088, v6
	ds_write2_b32 v0, v2, v3 offset1:1
	v_add_u32_e32 v0, 48, v17
	v_mad_i64_i32 v[0:1], s[14:15], v0, s2, v[4:5]
	global_load_dwordx4 v[0:3], v[0:1], off
	v_add_u32_e32 v4, 0x30c0, v6
	s_waitcnt vmcnt(0)
	ds_write2_b32 v4, v0, v1 offset1:1
	v_add_u32_e32 v0, 0x30c8, v6
	ds_write2_b32 v0, v2, v3 offset1:1
	v_and_b32_e32 v0, -4, v15
	v_mul_u32_u24_e32 v1, 0x41, v25
	v_lshl_add_u32 v2, v1, 2, v0
	s_waitcnt lgkmcnt(0)
	s_barrier
	ds_read2_b32 v[4:5], v2 offset1:65
	v_add_u32_e32 v3, 0x800, v2
	ds_read2_b32 v[16:17], v3 offset0:8 offset1:73
	ds_read2_b32 v[0:1], v2 offset0:130 offset1:195
	ds_read2_b32 v[18:19], v3 offset0:138 offset1:203
	v_add_u32_e32 v3, 0x400, v2
	ds_read2_b32 v[6:7], v3 offset0:4 offset1:69
	v_add_u32_e32 v15, 0xc00, v2
	s_waitcnt lgkmcnt(2)
	v_cvt_pk_bf16_f32 v1, v0, v1
	v_cvt_pk_bf16_f32 v0, v4, v5
	v_cvt_pk_bf16_f32 v4, v16, v17
	v_add_u32_e32 v16, s22, v24
	ds_read2_b32 v[20:21], v15 offset0:12 offset1:77
	ds_read2_b32 v[2:3], v3 offset0:134 offset1:199
	ds_read2_b32 v[22:23], v15 offset0:142 offset1:207
	v_ashrrev_i32_e32 v17, 31, v16
	v_lshlrev_b64 v[16:17], 11, v[16:17]
	v_lshl_add_u64 v[16:17], s[30:31], 0, v[16:17]
	s_waitcnt lgkmcnt(4)
	v_cvt_pk_bf16_f32 v5, v18, v19
	v_lshl_add_u64 v[16:17], s[20:21], 1, v[16:17]
	v_lshlrev_b32_e32 v18, 1, v25
	v_mov_b32_e32 v19, v149
	s_waitcnt lgkmcnt(1)
	v_cvt_pk_bf16_f32 v3, v2, v3
	v_cvt_pk_bf16_f32 v2, v6, v7
	v_lshl_add_u64 v[16:17], v[16:17], 0, v[18:19]
	s_waitcnt lgkmcnt(0)
	v_cvt_pk_bf16_f32 v7, v22, v23
	v_cvt_pk_bf16_f32 v6, v20, v21
	global_store_dwordx4 v[16:17], v[0:3], off sc1
	global_store_dwordx4 v[16:17], v[4:7], off offset:16 sc1
	s_branch .LBB0_613
